# SWA head loop: sink via s_load, wait for next head q prefetch moved from mid-head to its consumer (counted vmcnt(4) so O stores stay in flight); stacks on v7
# speedup vs baseline: 1.0010x; 1.0010x over previous
; __device__ __forceinline__ unsigned cvt_pk_bf16(float lo, float hi) { unsigned r; asm volatile("v_cvt_pk_bf16_f32 %0, %1, %2" : "=v"(r) : "v"(lo), "v"(hi)); return r; }
; __device__ __forceinline__ float bflo(unsigned w) { return __uint_as_float(w << 16); }
; __device__ __forceinline__ float bfhi(unsigned w) { return __uint_as_float(w & 0xffff0000u); }
; #define LAS __attribute__((address_space(3)))
; __device__ __forceinline__ void swa_compute(SwaRaw& R, int b, int kvh, int nb, const bf16_t* P, const float* __restrict__ qg, const float* __restrict__ kg, const float* __restrict__ sinks, bf16_t* OB, LAS unsigned char* lds, int tid) {
;     ...
;     {
;         const f32x4 g0 = *(const f32x4*)(kg + ch * 8), g1 = *(const f32x4*)(kg + ch * 8 + 4);
; #pragma unroll
;         for (int p = 0; p < 4; ++p) { const int ki = (tid >> 3) + 64 * p; const u32x4 raw = R.k[p], rv = R.v[p];
;             float x[8] = {bflo(raw.x), bfhi(raw.x), bflo(raw.y), bfhi(raw.y), bflo(raw.z), bfhi(raw.z), bflo(raw.w), bfhi(raw.w)};
;             float ss = 0.f;
; #pragma unroll
;             for (int e = 0; e < 8; ++e) ss += x[e] * x[e];
;             ss += __shfl_xor(ss, 1); ss += __shfl_xor(ss, 2); ss += __shfl_xor(ss, 4);
;             const float rs = 1.0f / sqrtf(ss * (1.0f / 64.0f) + EPS);
;             u32x4 w; w.x = cvt_pk_bf16(x[0] * rs * g0.x, x[1] * rs * g0.y); w.y = cvt_pk_bf16(x[2] * rs * g0.z, x[3] * rs * g0.w); w.z = cvt_pk_bf16(x[4] * rs * g1.x, x[5] * rs * g1.y); w.w = cvt_pk_bf16(x[6] * rs * g1.z, x[7] * rs * g1.w);
;             *(LAS u32x4*)(Ks + ki * 72 + ch * 8) = w;
;             *(LAS u32x4*)(Vr + ki * 72 + ch * 8) = rv; }
;     }
.LBB0_404:
	global_load_dwordx4 v[40:43], v[112:113], off offset:16
	s_nop 0
	global_load_dwordx4 v[44:47], v[112:113], off
	v_and_b32_e32 v50, 64, v199
	v_xor_b32_e32 v51, 1, v199
	v_add_u32_e32 v50, 64, v50
	v_cmp_lt_i32_e32 vcc, v51, v50
	v_and_b32_e32 v54, 0xffff0000, v36
	v_mul_f32_e32 v58, v54, v54
	v_cndmask_b32_e32 v51, v199, v51, vcc
	v_lshlrev_b32_e32 v60, 2, v51
	v_xor_b32_e32 v51, 2, v199
	v_cmp_lt_i32_e32 vcc, v51, v50
	v_lshlrev_b32_e32 v55, 16, v37
	v_and_b32_e32 v56, 0xffff0000, v37
	v_cndmask_b32_e32 v51, v199, v51, vcc
	v_lshlrev_b32_e32 v61, 2, v51
	v_xor_b32_e32 v51, 4, v199
	v_cmp_lt_i32_e32 vcc, v51, v50
	v_lshlrev_b32_e32 v57, 16, v38
	v_and_b32_e32 v38, 0xffff0000, v38
	v_cndmask_b32_e32 v51, v199, v51, vcc
	v_lshlrev_b32_e32 v62, 2, v51
	v_lshlrev_b32_e32 v51, 16, v36
	v_fmac_f32_e32 v58, v51, v51
	v_fmac_f32_e32 v58, v55, v55
	v_fmac_f32_e32 v58, v56, v56
	v_fmac_f32_e32 v58, v57, v57
	v_and_b32_e32 v52, 0xffff0000, v39
	v_lshlrev_b32_e32 v53, 16, v39
	v_fmac_f32_e32 v58, v38, v38
	v_pk_mul_f32 v[36:37], v[52:53], v[52:53]
	s_and_b32 s0, s18, 3
	v_add_f32_e32 v37, v37, v58
	v_add_f32_e32 v36, v36, v37
	ds_bpermute_b32 v37, v60, v36
	v_readlane_b32 s4, v236, 23
	s_lshl_b32 s2, s0, 4
	v_readlane_b32 s8, v236, 27
	v_readlane_b32 s9, v236, 28
	s_waitcnt lgkmcnt(0)
	v_add_f32_e32 v36, v36, v37
	ds_bpermute_b32 v37, v61, v36
	s_add_u32 s2, s8, s2
	v_readlane_b32 s5, v236, 24
	s_addc_u32 s3, s9, 0
	s_and_b32 s4, s39, 31
	s_waitcnt lgkmcnt(0)
	v_add_f32_e32 v36, v36, v37
	ds_bpermute_b32 v37, v62, v36
	s_lshl_b32 s96, s4, 7
	v_readlane_b32 s6, v236, 25
	v_readfirstlane_b32 s6, v186
	s_lshr_b32 s8, s6, 6
	s_waitcnt lgkmcnt(0)
	v_add_f32_e32 v36, v36, v37
	v_fmamk_f32 v36, v36, 0x3c800000, v196
	v_cmp_gt_f32_e32 vcc, s90, v36
	v_mul_f32_e32 v37, 0x4f800000, v36
	s_lshl_b32 s0, s0, 9
	v_cndmask_b32_e32 v36, v36, v37, vcc
	v_sqrt_f32_e32 v37, v36
	v_readlane_b32 s16, v236, 35
	v_readlane_b32 s7, v236, 26
	v_readlane_b32 s14, v236, 33
	v_add_u32_e32 v39, -1, v37
	v_fma_f32 v58, -v39, v37, v36
	v_cmp_ge_f32_e64 s[4:5], 0, v58
	v_add_u32_e32 v58, 1, v37
	s_mul_i32 s7, s8, 0x1500
	v_cndmask_b32_e64 v39, v37, v39, s[4:5]
	v_fma_f32 v37, -v58, v37, v36
	v_cmp_lt_f32_e64 s[4:5], 0, v37
	s_movk_i32 s14, 0x7f
	s_movk_i32 s76, 0x7e
	v_cndmask_b32_e64 v37, v39, v58, s[4:5]
	v_mul_f32_e32 v39, 0x37800000, v37
	v_cndmask_b32_e32 v37, v37, v39, vcc
	v_cmp_class_f32_e32 vcc, v36, v197
	v_readlane_b32 s10, v236, 29
	v_readlane_b32 s11, v236, 30
	v_cndmask_b32_e32 v36, v37, v36, vcc
	v_div_scale_f32 v37, s[4:5], v36, v36, 1.0
	v_rcp_f32_e32 v39, v37
	v_readlane_b32 s12, v236, 31
	v_readlane_b32 s13, v236, 32
	v_readlane_b32 s15, v236, 34
	v_fma_f32 v58, -v37, v39, 1.0
	v_fmac_f32_e32 v39, v58, v39
	v_div_scale_f32 v58, vcc, 1.0, v36, 1.0
	v_mul_f32_e32 v59, v58, v39
	v_fma_f32 v63, -v37, v59, v58
	v_fmac_f32_e32 v59, v63, v39
	v_fma_f32 v37, -v37, v59, v58
	v_div_fmas_f32 v37, v37, v39, v59
	v_div_fixup_f32 v39, v37, v36, 1.0
	v_mul_f32_e32 v36, v39, v51
	v_mul_f32_e32 v37, v39, v54
	s_waitcnt vmcnt(0)
	v_mul_f32_e32 v36, v44, v36
	v_mul_f32_e32 v37, v45, v37
	v_cvt_pk_bf16_f32 v36, v36, v37
	v_mul_f32_e32 v37, v39, v55
	v_mul_f32_e32 v51, v39, v56
	v_mul_f32_e32 v37, v46, v37
	v_mul_f32_e32 v51, v47, v51
	v_cvt_pk_bf16_f32 v37, v37, v51
	v_mul_f32_e32 v51, v39, v57
	v_mul_f32_e32 v38, v39, v38
	v_mul_f32_e32 v51, v40, v51
	v_mul_f32_e32 v38, v41, v38
	v_cvt_pk_bf16_f32 v38, v51, v38
	v_mul_f32_e32 v51, v39, v53
	v_mul_f32_e32 v39, v39, v52
	v_mul_f32_e32 v39, v43, v39
	v_mul_f32_e32 v51, v42, v51
	v_cvt_pk_bf16_f32 v39, v51, v39
	ds_write_b128 v93, v[36:39] offset:18432
	ds_write_b128 v93, v[32:35] offset:55296
	v_and_b32_e32 v35, 0xffff0000, v28
	v_lshlrev_b32_e32 v34, 16, v28
	v_mul_f32_e32 v39, v35, v35
	v_lshlrev_b32_e32 v36, 16, v29
	v_fmac_f32_e32 v39, v34, v34
	v_and_b32_e32 v37, 0xffff0000, v29
	v_fmac_f32_e32 v39, v36, v36
	v_lshlrev_b32_e32 v38, 16, v30
	v_fmac_f32_e32 v39, v37, v37
	v_and_b32_e32 v30, 0xffff0000, v30
	v_fmac_f32_e32 v39, v38, v38
	v_and_b32_e32 v32, 0xffff0000, v31
	v_lshlrev_b32_e32 v33, 16, v31
	v_fmac_f32_e32 v39, v30, v30
	v_pk_mul_f32 v[28:29], v[32:33], v[32:33]
	v_add_u32_e32 v63, s7, v195
	v_add_f32_e32 v29, v29, v39
	v_add_f32_e32 v28, v28, v29
	ds_bpermute_b32 v29, v60, v28
	v_readlane_b32 s17, v236, 36
	v_readlane_b32 s18, v236, 37
	v_readlane_b32 s19, v236, 38
	v_writelane_b32 v235, s39, 9
	s_waitcnt lgkmcnt(0)
	v_add_f32_e32 v28, v28, v29
	ds_bpermute_b32 v29, v61, v28
	v_mov_b32_e32 v48, s0
	v_mov_b32_e32 v49, v99
	s_waitcnt lgkmcnt(0)
	v_add_f32_e32 v28, v28, v29
	ds_bpermute_b32 v29, v62, v28
	s_waitcnt lgkmcnt(0)
; __device__ __forceinline__ unsigned cvt_pk_bf16(float lo, float hi) { unsigned r; asm volatile("v_cvt_pk_bf16_f32 %0, %1, %2" : "=v"(r) : "v"(lo), "v"(hi)); return r; }
; __device__ __forceinline__ float bflo(unsigned w) { return __uint_as_float(w << 16); }
; __device__ __forceinline__ float bfhi(unsigned w) { return __uint_as_float(w & 0xffff0000u); }
; #define LAS __attribute__((address_space(3)))
; __device__ __forceinline__ void swa_compute(SwaRaw& R, int b, int kvh, int nb, const bf16_t* P, const float* __restrict__ qg, const float* __restrict__ kg, const float* __restrict__ sinks, bf16_t* OB, LAS unsigned char* lds, int tid) {
;     ...
;         for (int p = 0; p < 4; ++p) { const int ki = (tid >> 3) + 64 * p; const u32x4 raw = R.k[p], rv = R.v[p];
;             float x[8] = {bflo(raw.x), bfhi(raw.x), bflo(raw.y), bfhi(raw.y), bflo(raw.z), bfhi(raw.z), bflo(raw.w), bfhi(raw.w)};
;             float ss = 0.f;
; #pragma unroll
;             for (int e = 0; e < 8; ++e) ss += x[e] * x[e];
;             ss += __shfl_xor(ss, 1); ss += __shfl_xor(ss, 2); ss += __shfl_xor(ss, 4);
;             const float rs = 1.0f / sqrtf(ss * (1.0f / 64.0f) + EPS);
;             u32x4 w; w.x = cvt_pk_bf16(x[0] * rs * g0.x, x[1] * rs * g0.y); w.y = cvt_pk_bf16(x[2] * rs * g0.z, x[3] * rs * g0.w); w.z = cvt_pk_bf16(x[4] * rs * g1.x, x[5] * rs * g1.y); w.w = cvt_pk_bf16(x[6] * rs * g1.z, x[7] * rs * g1.w);
;             *(LAS u32x4*)(Ks + ki * 72 + ch * 8) = w;
;             *(LAS u32x4*)(Vr + ki * 72 + ch * 8) = rv; }
	v_add_f32_e32 v28, v28, v29
	v_fmamk_f32 v28, v28, 0x3c800000, v196
	v_cmp_gt_f32_e32 vcc, s90, v28
	v_mul_f32_e32 v29, 0x4f800000, v28
	s_nop 0
	v_cndmask_b32_e32 v28, v28, v29, vcc
	v_sqrt_f32_e32 v29, v28
	s_nop 0
	v_add_u32_e32 v31, -1, v29
	v_fma_f32 v39, -v31, v29, v28
	v_cmp_ge_f32_e64 s[4:5], 0, v39
	v_add_u32_e32 v39, 1, v29
	s_nop 0
	v_cndmask_b32_e64 v31, v29, v31, s[4:5]
	v_fma_f32 v29, -v39, v29, v28
	v_cmp_lt_f32_e64 s[4:5], 0, v29
	s_nop 1
	v_cndmask_b32_e64 v29, v31, v39, s[4:5]
	v_mul_f32_e32 v31, 0x37800000, v29
	v_cndmask_b32_e32 v29, v29, v31, vcc
	v_cmp_class_f32_e32 vcc, v28, v197
	s_nop 1
	v_cndmask_b32_e32 v28, v29, v28, vcc
	v_div_scale_f32 v29, s[4:5], v28, v28, 1.0
	v_rcp_f32_e32 v31, v29
	s_nop 0
	v_fma_f32 v39, -v29, v31, 1.0
	v_fmac_f32_e32 v31, v39, v31
	v_div_scale_f32 v39, vcc, 1.0, v28, 1.0
	v_mul_f32_e32 v51, v39, v31
	v_fma_f32 v52, -v29, v51, v39
	v_fmac_f32_e32 v51, v52, v31
	v_fma_f32 v29, -v29, v51, v39
	v_div_fmas_f32 v29, v29, v31, v51
	v_div_fixup_f32 v31, v29, v28, 1.0
	v_mul_f32_e32 v28, v31, v34
	v_mul_f32_e32 v29, v31, v35
	v_mul_f32_e32 v28, v44, v28
	v_mul_f32_e32 v29, v45, v29
	v_cvt_pk_bf16_f32 v28, v28, v29
	v_mul_f32_e32 v29, v31, v36
	v_mul_f32_e32 v34, v31, v37
	v_mul_f32_e32 v29, v46, v29
	v_mul_f32_e32 v34, v47, v34
	v_cvt_pk_bf16_f32 v29, v29, v34
	v_mul_f32_e32 v34, v31, v38
	v_mul_f32_e32 v30, v31, v30
	v_mul_f32_e32 v33, v31, v33
	v_mul_f32_e32 v31, v31, v32
	v_mul_f32_e32 v30, v41, v30
	v_mul_f32_e32 v31, v43, v31
	v_mul_f32_e32 v34, v40, v34
	v_cvt_pk_bf16_f32 v30, v34, v30
	v_mul_f32_e32 v33, v42, v33
	v_cvt_pk_bf16_f32 v31, v33, v31
	ds_write_b128 v93, v[28:31] offset:27648
	ds_write_b128 v93, v[24:27] offset:64512
	v_and_b32_e32 v27, 0xffff0000, v20
	v_lshlrev_b32_e32 v26, 16, v20
	v_mul_f32_e32 v31, v27, v27
	v_lshlrev_b32_e32 v28, 16, v21
	v_fmac_f32_e32 v31, v26, v26
	v_and_b32_e32 v29, 0xffff0000, v21
	v_fmac_f32_e32 v31, v28, v28
	v_lshlrev_b32_e32 v30, 16, v22
	v_fmac_f32_e32 v31, v29, v29
	v_and_b32_e32 v22, 0xffff0000, v22
	v_fmac_f32_e32 v31, v30, v30
	v_and_b32_e32 v24, 0xffff0000, v23
	v_lshlrev_b32_e32 v25, 16, v23
	v_fmac_f32_e32 v31, v22, v22
	v_pk_mul_f32 v[20:21], v[24:25], v[24:25]
	s_nop 0
	v_add_f32_e32 v21, v21, v31
	v_add_f32_e32 v20, v20, v21
	ds_bpermute_b32 v21, v60, v20
	s_waitcnt lgkmcnt(0)
	v_add_f32_e32 v20, v20, v21
	ds_bpermute_b32 v21, v61, v20
	s_waitcnt lgkmcnt(0)
	v_add_f32_e32 v20, v20, v21
	ds_bpermute_b32 v21, v62, v20
	s_waitcnt lgkmcnt(0)
	v_add_f32_e32 v20, v20, v21
	v_fmamk_f32 v20, v20, 0x3c800000, v196
	v_cmp_gt_f32_e32 vcc, s90, v20
	v_mul_f32_e32 v21, 0x4f800000, v20
	s_nop 0
	v_cndmask_b32_e32 v20, v20, v21, vcc
	v_sqrt_f32_e32 v21, v20
	s_nop 0
	v_add_u32_e32 v23, -1, v21
	v_fma_f32 v31, -v23, v21, v20
	v_cmp_ge_f32_e64 s[4:5], 0, v31
	v_add_u32_e32 v31, 1, v21
	s_nop 0
	v_cndmask_b32_e64 v23, v21, v23, s[4:5]
	v_fma_f32 v21, -v31, v21, v20
	v_cmp_lt_f32_e64 s[4:5], 0, v21
	s_nop 1
	v_cndmask_b32_e64 v21, v23, v31, s[4:5]
	v_mul_f32_e32 v23, 0x37800000, v21
	v_cndmask_b32_e32 v21, v21, v23, vcc
	v_cmp_class_f32_e32 vcc, v20, v197
	s_nop 1
	v_cndmask_b32_e32 v20, v21, v20, vcc
	v_div_scale_f32 v21, s[4:5], v20, v20, 1.0
	v_rcp_f32_e32 v23, v21
	s_nop 0
	v_fma_f32 v31, -v21, v23, 1.0
	v_fmac_f32_e32 v23, v31, v23
	v_div_scale_f32 v31, vcc, 1.0, v20, 1.0
	v_mul_f32_e32 v32, v31, v23
	v_fma_f32 v33, -v21, v32, v31
	v_fmac_f32_e32 v32, v33, v23
	v_fma_f32 v21, -v21, v32, v31
	v_div_fmas_f32 v21, v21, v23, v32
	v_div_fixup_f32 v23, v21, v20, 1.0
	v_mul_f32_e32 v20, v23, v26
	v_mul_f32_e32 v21, v23, v27
	v_mul_f32_e32 v20, v44, v20
	v_mul_f32_e32 v21, v45, v21
	v_cvt_pk_bf16_f32 v20, v20, v21
	v_mul_f32_e32 v21, v23, v28
	v_mul_f32_e32 v26, v23, v29
	v_mul_f32_e32 v21, v46, v21
	v_mul_f32_e32 v26, v47, v26
	v_cvt_pk_bf16_f32 v21, v21, v26
	v_mul_f32_e32 v26, v23, v30
	v_mul_f32_e32 v22, v23, v22
	v_mul_f32_e32 v25, v23, v25
	v_mul_f32_e32 v23, v23, v24
	v_mul_f32_e32 v22, v41, v22
	v_mul_f32_e32 v23, v43, v23
	v_mul_f32_e32 v26, v40, v26
	v_cvt_pk_bf16_f32 v22, v26, v22
	v_mul_f32_e32 v25, v42, v25
	v_cvt_pk_bf16_f32 v23, v25, v23
	ds_write_b128 v93, v[20:23] offset:36864
	ds_write_b128 v191, v[16:19] offset:18432
	v_and_b32_e32 v19, 0xffff0000, v12
	v_lshlrev_b32_e32 v18, 16, v12
	v_mul_f32_e32 v23, v19, v19
	v_lshlrev_b32_e32 v20, 16, v13
	v_fmac_f32_e32 v23, v18, v18
	v_and_b32_e32 v21, 0xffff0000, v13
	v_fmac_f32_e32 v23, v20, v20
	v_lshlrev_b32_e32 v22, 16, v14
	v_fmac_f32_e32 v23, v21, v21
	v_and_b32_e32 v14, 0xffff0000, v14
	v_fmac_f32_e32 v23, v22, v22
	v_and_b32_e32 v16, 0xffff0000, v15
	v_lshlrev_b32_e32 v17, 16, v15
	v_fmac_f32_e32 v23, v14, v14
	v_pk_mul_f32 v[12:13], v[16:17], v[16:17]
	s_nop 0
	v_add_f32_e32 v13, v13, v23
	v_add_f32_e32 v12, v12, v13
	ds_bpermute_b32 v13, v60, v12
	s_waitcnt lgkmcnt(0)
	v_add_f32_e32 v12, v12, v13
	ds_bpermute_b32 v13, v61, v12
	s_waitcnt lgkmcnt(0)
	v_add_f32_e32 v12, v12, v13
	ds_bpermute_b32 v13, v62, v12
	s_waitcnt lgkmcnt(0)
; __device__ __forceinline__ unsigned cvt_pk_bf16(float lo, float hi) { unsigned r; asm volatile("v_cvt_pk_bf16_f32 %0, %1, %2" : "=v"(r) : "v"(lo), "v"(hi)); return r; }
; __device__ __forceinline__ float bflo(unsigned w) { return __uint_as_float(w << 16); }
; __device__ __forceinline__ float bfhi(unsigned w) { return __uint_as_float(w & 0xffff0000u); }
; #define LAS __attribute__((address_space(3)))
; __device__ __forceinline__ void swa_compute(SwaRaw& R, int b, int kvh, int nb, const bf16_t* P, const float* __restrict__ qg, const float* __restrict__ kg, const float* __restrict__ sinks, bf16_t* OB, LAS unsigned char* lds, int tid) {
;     ...
;         for (int p = 0; p < 4; ++p) { const int ki = (tid >> 3) + 64 * p; const u32x4 raw = R.k[p], rv = R.v[p];
;             float x[8] = {bflo(raw.x), bfhi(raw.x), bflo(raw.y), bfhi(raw.y), bflo(raw.z), bfhi(raw.z), bflo(raw.w), bfhi(raw.w)};
;             float ss = 0.f;
; #pragma unroll
;             for (int e = 0; e < 8; ++e) ss += x[e] * x[e];
;             ss += __shfl_xor(ss, 1); ss += __shfl_xor(ss, 2); ss += __shfl_xor(ss, 4);
;             const float rs = 1.0f / sqrtf(ss * (1.0f / 64.0f) + EPS);
;             u32x4 w; w.x = cvt_pk_bf16(x[0] * rs * g0.x, x[1] * rs * g0.y); w.y = cvt_pk_bf16(x[2] * rs * g0.z, x[3] * rs * g0.w); w.z = cvt_pk_bf16(x[4] * rs * g1.x, x[5] * rs * g1.y); w.w = cvt_pk_bf16(x[6] * rs * g1.z, x[7] * rs * g1.w);
;             *(LAS u32x4*)(Ks + ki * 72 + ch * 8) = w;
;             *(LAS u32x4*)(Vr + ki * 72 + ch * 8) = rv; }
;     }
;     const f32x4 qg0 = *(const f32x4*)(qg + ch * 8), qg1 = *(const f32x4*)(qg + ch * 8 + 4);
;     const int kt0 = wid > 0 ? wid - 1 : 0;
;     ...
;         const int qi = wid * 16 + fr; const float sink = sinks[hq]; float m = sink;
; #pragma unroll
;         for (int j = 0; j < 10; ++j)
; #pragma unroll
;             for (int r = 0; r < 4; ++r) { const int ki = (kt0 + j) * 16 + 4 * fq + r; const bool valid = (ki > qi) && (ki <= qi + 128) && ((nb > 0) || (ki >= 128));
;                 s[j][r] = valid ? s[j][r] : -INFINITY; m = fmaxf(m, s[j][r]); }
	v_add_f32_e32 v12, v12, v13
	v_fmamk_f32 v12, v12, 0x3c800000, v196
	v_cmp_gt_f32_e32 vcc, s90, v12
	v_mul_f32_e32 v13, 0x4f800000, v12
	s_nop 0
	v_cndmask_b32_e32 v12, v12, v13, vcc
	v_sqrt_f32_e32 v13, v12
	s_nop 0
	v_add_u32_e32 v15, -1, v13
	v_fma_f32 v23, -v15, v13, v12
	v_cmp_ge_f32_e64 s[4:5], 0, v23
	v_add_u32_e32 v23, 1, v13
	s_nop 0
	v_cndmask_b32_e64 v15, v13, v15, s[4:5]
	v_fma_f32 v13, -v23, v13, v12
	v_cmp_lt_f32_e64 s[4:5], 0, v13
	s_nop 1
	v_cndmask_b32_e64 v13, v15, v23, s[4:5]
	v_mul_f32_e32 v15, 0x37800000, v13
	v_cndmask_b32_e32 v13, v13, v15, vcc
	v_cmp_class_f32_e32 vcc, v12, v197
	s_nop 1
	v_cndmask_b32_e32 v12, v13, v12, vcc
	v_div_scale_f32 v13, s[4:5], v12, v12, 1.0
	v_rcp_f32_e32 v15, v13
	s_lshl_b32 s4, s8, 4
	s_movk_i32 s5, 0x90
	v_fma_f32 v23, -v13, v15, 1.0
	v_fmac_f32_e32 v15, v23, v15
	v_div_scale_f32 v23, vcc, 1.0, v12, 1.0
	v_mul_f32_e32 v24, v23, v15
	v_fma_f32 v25, -v13, v24, v23
	v_fmac_f32_e32 v24, v25, v15
	v_fma_f32 v13, -v13, v24, v23
	v_div_fmas_f32 v13, v13, v15, v24
	v_div_fixup_f32 v15, v13, v12, 1.0
	v_mul_f32_e32 v12, v15, v18
	v_mul_f32_e32 v13, v15, v19
	v_mul_f32_e32 v12, v44, v12
	v_mul_f32_e32 v13, v45, v13
	v_cvt_pk_bf16_f32 v12, v12, v13
	v_mul_f32_e32 v13, v15, v20
	v_mul_f32_e32 v18, v15, v21
	v_mul_f32_e32 v13, v46, v13
	v_mul_f32_e32 v18, v47, v18
	v_cvt_pk_bf16_f32 v13, v13, v18
	v_mul_f32_e32 v18, v15, v22
	v_mul_f32_e32 v14, v15, v14
	v_mul_f32_e32 v17, v15, v17
	v_mul_f32_e32 v15, v15, v16
	v_or_b32_e32 v16, s4, v91
	s_add_i32 s4, s4, -16
	s_cmp_gt_u32 s6, 63
	s_cselect_b32 s4, s4, 0
	v_mul_f32_e32 v14, v41, v14
	v_mul_f32_e32 v17, v42, v17
	v_mul_f32_e32 v15, v43, v15
	v_add_u32_e32 v19, s4, v192
	s_add_i32 s16, s4, 16
	s_add_i32 s24, s4, 32
	s_add_i32 s34, s4, 48
	s_add_i32 s42, s4, 64
	s_add_i32 s50, s4, 0x50
	s_add_i32 s58, s4, 0x60
	s_add_i32 s66, s4, 0x70
	v_sub_co_u32_e32 v29, vcc, s4, v200
	s_add_i32 s78, s4, 0x90
	v_mul_f32_e32 v18, v40, v18
	v_cvt_pk_bf16_f32 v14, v18, v14
	v_cvt_pk_bf16_f32 v15, v17, v15
	v_add_u32_e32 v17, 0x80, v16
	v_mul_lo_u32 v64, v19, s5
	v_or_b32_e32 v19, s4, v91
	v_or_b32_e32 v20, s16, v91
	v_or_b32_e32 v21, s24, v91
	v_or_b32_e32 v22, s34, v91
	v_or_b32_e32 v23, s42, v91
	v_or_b32_e32 v24, s50, v91
	v_or_b32_e32 v25, s58, v91
	v_or_b32_e32 v26, s66, v91
	v_or_b32_e32 v27, v29, v91
	v_or_b32_e32 v28, s78, v91
	v_or_b32_e32 v30, s4, v161
	v_mul_lo_u32 v18, v16, s5
	v_mul_lo_u32 v19, v19, s5
	v_mul_lo_u32 v20, v20, s5
	v_mul_lo_u32 v21, v21, s5
	v_mul_lo_u32 v22, v22, s5
	v_mul_lo_u32 v23, v23, s5
	v_mul_lo_u32 v24, v24, s5
	v_mul_lo_u32 v25, v25, s5
	v_mul_lo_u32 v26, v26, s5
	v_mul_lo_u32 v27, v27, s5
	v_mul_lo_u32 v28, v28, s5
	v_cmp_gt_i32_e64 s[4:5], v30, v16
	v_cmp_le_i32_e64 s[6:7], v30, v17
	s_and_b64 s[6:7], s[4:5], s[6:7]
	v_cmp_lt_i32_e64 s[4:5], s14, v30
	s_or_b64 s[4:5], s[74:75], s[4:5]
	s_and_b64 s[4:5], s[6:7], s[4:5]
	v_cmp_ge_i32_e64 s[6:7], v30, v16
	v_cmp_lt_i32_e64 s[8:9], v30, v17
	s_and_b64 s[8:9], s[6:7], s[8:9]
	v_cmp_lt_i32_e64 s[6:7], s76, v30
	s_or_b64 s[6:7], s[74:75], s[6:7]
	v_or_b32_e32 v31, 2, v30
	s_and_b64 s[6:7], s[8:9], s[6:7]
	v_cmp_gt_i32_e64 s[8:9], v31, v16
	v_cmp_le_i32_e64 s[10:11], v31, v17
	s_and_b64 s[10:11], s[8:9], s[10:11]
	v_cmp_lt_i32_e64 s[8:9], s14, v31
	s_or_b64 s[8:9], s[74:75], s[8:9]
	v_or_b32_e32 v30, 3, v30
	s_and_b64 s[8:9], s[10:11], s[8:9]
	v_cmp_gt_i32_e64 s[10:11], v30, v16
	v_cmp_le_i32_e64 s[12:13], v30, v17
	s_and_b64 s[12:13], s[10:11], s[12:13]
	v_cmp_lt_i32_e64 s[10:11], s14, v30
	s_or_b64 s[10:11], s[74:75], s[10:11]
	v_or_b32_e32 v30, s16, v161
	s_and_b64 s[10:11], s[12:13], s[10:11]
	v_cmp_gt_i32_e64 s[12:13], v30, v16
	v_cmp_le_i32_e64 s[14:15], v30, v17
	s_and_b64 s[12:13], s[12:13], s[14:15]
	s_cmpk_gt_u32 s16, 0x7f
	s_cselect_b64 s[14:15], -1, 0
	s_or_b64 s[22:23], s[74:75], s[14:15]
	v_cmp_ge_i32_e64 s[14:15], v30, v16
	v_cmp_lt_i32_e64 s[16:17], v30, v17
	s_and_b64 s[16:17], s[14:15], s[16:17]
	v_cmp_lt_u32_e64 s[14:15], s76, v30
	s_or_b64 s[14:15], s[74:75], s[14:15]
	v_or_b32_e32 v31, 2, v30
	s_and_b64 s[14:15], s[16:17], s[14:15]
	v_cmp_gt_i32_e64 s[16:17], v31, v16
	v_cmp_le_i32_e64 s[18:19], v31, v17
	v_or_b32_e32 v30, 3, v30
	s_and_b64 s[16:17], s[16:17], s[18:19]
	v_cmp_gt_i32_e64 s[18:19], v30, v16
	v_cmp_le_i32_e64 s[20:21], v30, v17
	ds_write_b128 v93, v[12:15] offset:46080
	ds_write_b128 v191, v[8:11] offset:27648
	s_and_b64 s[18:19], s[18:19], s[20:21]
	v_or_b32_e32 v30, s24, v161
	global_load_dwordx4 v[8:11], v[114:115], off
	global_load_dwordx4 v[12:15], v[114:115], off offset:16
	s_and_b64 s[12:13], s[22:23], s[12:13]
	s_and_b64 s[16:17], s[22:23], s[16:17]
	s_and_b64 s[18:19], s[22:23], s[18:19]
	v_cmp_gt_i32_e64 s[20:21], v30, v16
	v_cmp_le_i32_e64 s[22:23], v30, v17
	s_and_b64 s[20:21], s[20:21], s[22:23]
	s_cmpk_gt_u32 s24, 0x7f
	s_cselect_b64 s[22:23], -1, 0
	s_or_b64 s[30:31], s[74:75], s[22:23]
	v_cmp_ge_i32_e64 s[22:23], v30, v16
	v_cmp_lt_i32_e64 s[24:25], v30, v17
	s_and_b64 s[24:25], s[22:23], s[24:25]
	v_cmp_lt_u32_e64 s[22:23], s76, v30
	s_or_b64 s[22:23], s[74:75], s[22:23]
	v_or_b32_e32 v31, 2, v30
	s_and_b64 s[22:23], s[24:25], s[22:23]
	v_cmp_gt_i32_e64 s[24:25], v31, v16
	v_cmp_le_i32_e64 s[26:27], v31, v17
	v_or_b32_e32 v30, 3, v30
	s_and_b64 s[24:25], s[24:25], s[26:27]
	v_cmp_gt_i32_e64 s[26:27], v30, v16
	v_cmp_le_i32_e64 s[28:29], v30, v17
	s_and_b64 s[26:27], s[26:27], s[28:29]
	v_or_b32_e32 v30, s34, v161
	s_and_b64 s[20:21], s[30:31], s[20:21]
	s_and_b64 s[24:25], s[30:31], s[24:25]
	s_and_b64 s[26:27], s[30:31], s[26:27]
	v_cmp_gt_i32_e64 s[28:29], v30, v16
	v_cmp_le_i32_e64 s[30:31], v30, v17
	s_and_b64 s[28:29], s[28:29], s[30:31]
; __device__ __forceinline__ unsigned cvt_pk_bf16(float lo, float hi) { unsigned r; asm volatile("v_cvt_pk_bf16_f32 %0, %1, %2" : "=v"(r) : "v"(lo), "v"(hi)); return r; }
; #define LAS __attribute__((address_space(3)))
; #define MFMA16(a, b, c) __builtin_amdgcn_mfma_f32_16x16x32_bf16((a), (b), (c), 0, 0, 0)
; __device__ __forceinline__ void swa_compute(SwaRaw& R, int b, int kvh, int nb, const bf16_t* P, const float* __restrict__ qg, const float* __restrict__ kg, const float* __restrict__ sinks, bf16_t* OB, LAS unsigned char* lds, int tid) {
;     ...
;         const int qi = wid * 16 + fr; const float sink = sinks[hq]; float m = sink;
; #pragma unroll
;         for (int j = 0; j < 10; ++j)
; #pragma unroll
;             for (int r = 0; r < 4; ++r) { const int ki = (kt0 + j) * 16 + 4 * fq + r; const bool valid = (ki > qi) && (ki <= qi + 128) && ((nb > 0) || (ki >= 128));
;                 s[j][r] = valid ? s[j][r] : -INFINITY; m = fmaxf(m, s[j][r]); }
;     ...
;             for (int ks = 0; ks < 5; ++ks) { const LAS bf16_t* vp = Vr + (kt0 * 16 + ks * 32 + 8 * fq + (fr >> 2)) * 72 + dt * 16 + 4 * (fr & 3);
;                 const v4i16_t lo = __builtin_amdgcn_ds_read_tr16_b64_v4i16((LAS v4i16_t*)vp), hi = __builtin_amdgcn_ds_read_tr16_b64_v4i16((LAS v4i16_t*)(vp + 4 * 72));
;                 const bf16x8 vf = {lo[0], lo[1], lo[2], lo[3], hi[0], hi[1], hi[2], hi[3]};
;                 acc = MFMA16(vf, ldfrag(Pw, 168, fr, ks * 32 + 8 * fq), acc); }
;             u32x2 w; w.x = cvt_pk_bf16(acc[0] * inv, acc[1] * inv); w.y = cvt_pk_bf16(acc[2] * inv, acc[3] * inv);
;             *(u32x2*)(OB + (rq0 + qi) * 1024 + hq * 64 + dt * 16 + 4 * fq) = w; }
	s_cmpk_gt_u32 s34, 0x7f
	s_cselect_b64 s[30:31], -1, 0
	s_or_b64 s[40:41], s[74:75], s[30:31]
	v_cmp_ge_i32_e64 s[30:31], v30, v16
	v_cmp_lt_i32_e64 s[34:35], v30, v17
	s_and_b64 s[34:35], s[30:31], s[34:35]
	v_cmp_lt_u32_e64 s[30:31], s76, v30
	s_or_b64 s[30:31], s[74:75], s[30:31]
	v_or_b32_e32 v31, 2, v30
	s_and_b64 s[30:31], s[34:35], s[30:31]
	v_cmp_gt_i32_e64 s[34:35], v31, v16
	v_cmp_le_i32_e64 s[36:37], v31, v17
	v_or_b32_e32 v30, 3, v30
	s_and_b64 s[34:35], s[34:35], s[36:37]
	v_cmp_gt_i32_e64 s[36:37], v30, v16
	v_cmp_le_i32_e64 s[38:39], v30, v17
	s_and_b64 s[36:37], s[36:37], s[38:39]
	v_or_b32_e32 v30, s42, v161
	s_and_b64 s[28:29], s[40:41], s[28:29]
	s_and_b64 s[34:35], s[40:41], s[34:35]
	s_and_b64 s[36:37], s[40:41], s[36:37]
	v_cmp_gt_i32_e64 s[38:39], v30, v16
	v_cmp_le_i32_e64 s[40:41], v30, v17
	s_and_b64 s[38:39], s[38:39], s[40:41]
	s_cmpk_gt_u32 s42, 0x7f
	s_cselect_b64 s[40:41], -1, 0
	s_or_b64 s[48:49], s[74:75], s[40:41]
	v_cmp_ge_i32_e64 s[40:41], v30, v16
	v_cmp_lt_i32_e64 s[42:43], v30, v17
	s_and_b64 s[42:43], s[40:41], s[42:43]
	v_cmp_lt_u32_e64 s[40:41], s76, v30
	s_or_b64 s[40:41], s[74:75], s[40:41]
	v_or_b32_e32 v31, 2, v30
	s_and_b64 s[40:41], s[42:43], s[40:41]
	v_cmp_gt_i32_e64 s[42:43], v31, v16
	v_cmp_le_i32_e64 s[44:45], v31, v17
	v_or_b32_e32 v30, 3, v30
	s_and_b64 s[42:43], s[42:43], s[44:45]
	v_cmp_gt_i32_e64 s[44:45], v30, v16
	v_cmp_le_i32_e64 s[46:47], v30, v17
	s_and_b64 s[44:45], s[44:45], s[46:47]
	v_or_b32_e32 v30, s50, v161
	s_and_b64 s[38:39], s[48:49], s[38:39]
	s_and_b64 s[42:43], s[48:49], s[42:43]
	s_and_b64 s[44:45], s[48:49], s[44:45]
	v_cmp_gt_i32_e64 s[46:47], v30, v16
	v_cmp_le_i32_e64 s[48:49], v30, v17
	s_and_b64 s[46:47], s[46:47], s[48:49]
	s_cmpk_gt_u32 s50, 0x7f
	s_cselect_b64 s[48:49], -1, 0
	s_or_b64 s[56:57], s[74:75], s[48:49]
	v_cmp_ge_i32_e64 s[48:49], v30, v16
	v_cmp_lt_i32_e64 s[50:51], v30, v17
	s_and_b64 s[50:51], s[48:49], s[50:51]
	v_cmp_lt_u32_e64 s[48:49], s76, v30
	s_or_b64 s[48:49], s[74:75], s[48:49]
	v_or_b32_e32 v31, 2, v30
	s_and_b64 s[48:49], s[50:51], s[48:49]
	v_cmp_gt_i32_e64 s[50:51], v31, v16
	v_cmp_le_i32_e64 s[52:53], v31, v17
	v_or_b32_e32 v30, 3, v30
	s_and_b64 s[50:51], s[50:51], s[52:53]
	v_cmp_gt_i32_e64 s[52:53], v30, v16
	v_cmp_le_i32_e64 s[54:55], v30, v17
	s_and_b64 s[52:53], s[52:53], s[54:55]
	v_or_b32_e32 v30, s58, v161
	s_and_b64 s[46:47], s[56:57], s[46:47]
	s_and_b64 s[50:51], s[56:57], s[50:51]
	s_and_b64 s[52:53], s[56:57], s[52:53]
	v_cmp_gt_i32_e64 s[54:55], v30, v16
	v_cmp_le_i32_e64 s[56:57], v30, v17
	s_and_b64 s[54:55], s[54:55], s[56:57]
	s_cmpk_gt_u32 s58, 0x7f
	s_cselect_b64 s[56:57], -1, 0
	s_or_b64 s[64:65], s[74:75], s[56:57]
	v_cmp_ge_i32_e64 s[56:57], v30, v16
	v_cmp_lt_i32_e64 s[58:59], v30, v17
	s_and_b64 s[58:59], s[56:57], s[58:59]
	v_cmp_lt_u32_e64 s[56:57], s76, v30
	s_or_b64 s[56:57], s[74:75], s[56:57]
	v_or_b32_e32 v31, 2, v30
	s_and_b64 s[56:57], s[58:59], s[56:57]
	v_cmp_gt_i32_e64 s[58:59], v31, v16
	v_cmp_le_i32_e64 s[60:61], v31, v17
	v_or_b32_e32 v30, 3, v30
	s_and_b64 s[58:59], s[58:59], s[60:61]
	v_cmp_gt_i32_e64 s[60:61], v30, v16
	v_cmp_le_i32_e64 s[62:63], v30, v17
	s_and_b64 s[60:61], s[60:61], s[62:63]
	v_or_b32_e32 v30, s66, v161
	s_and_b64 s[54:55], s[64:65], s[54:55]
	s_and_b64 s[58:59], s[64:65], s[58:59]
	s_and_b64 s[60:61], s[64:65], s[60:61]
	v_cmp_gt_i32_e64 s[62:63], v30, v16
	v_cmp_le_i32_e64 s[64:65], v30, v17
	s_and_b64 s[62:63], s[62:63], s[64:65]
	s_cmpk_gt_u32 s66, 0x7f
	s_cselect_b64 s[64:65], -1, 0
	s_or_b64 s[72:73], s[74:75], s[64:65]
	v_cmp_ge_i32_e64 s[64:65], v30, v16
	v_cmp_lt_i32_e64 s[66:67], v30, v17
	s_and_b64 s[66:67], s[64:65], s[66:67]
	v_cmp_lt_u32_e64 s[64:65], s76, v30
	s_or_b64 s[64:65], s[74:75], s[64:65]
	v_or_b32_e32 v31, 2, v30
	s_and_b64 s[64:65], s[66:67], s[64:65]
	v_cmp_gt_i32_e64 s[66:67], v31, v16
	v_cmp_le_i32_e64 s[68:69], v31, v17
	v_or_b32_e32 v30, 3, v30
	s_and_b64 s[66:67], s[66:67], s[68:69]
	v_cmp_gt_i32_e64 s[68:69], v30, v16
	v_cmp_le_i32_e64 s[70:71], v30, v17
	s_and_b64 s[68:69], s[68:69], s[70:71]
	v_or_b32_e32 v29, v29, v161
	s_and_b64 s[62:63], s[72:73], s[62:63]
	s_and_b64 s[66:67], s[72:73], s[66:67]
	s_and_b64 s[68:69], s[72:73], s[68:69]
	v_cmp_gt_i32_e64 s[70:71], v29, v16
	v_cmp_le_i32_e64 s[72:73], v29, v17
	s_and_b64 s[70:71], s[70:71], s[72:73]
	s_or_b64 s[80:81], s[74:75], vcc
	v_cmp_ge_i32_e32 vcc, v29, v16
	v_cmp_lt_i32_e64 s[72:73], v29, v17
	s_and_b64 s[72:73], vcc, s[72:73]
	v_cmp_lt_u32_e32 vcc, s76, v29
	s_or_b64 s[74:75], s[74:75], vcc
	v_or_b32_e32 v30, 2, v29
	s_and_b64 s[72:73], s[72:73], s[74:75]
	v_cmp_gt_i32_e32 vcc, v30, v16
	v_cmp_le_i32_e64 s[74:75], v30, v17
	v_or_b32_e32 v29, 3, v29
	s_and_b64 s[74:75], vcc, s[74:75]
	v_cmp_gt_i32_e32 vcc, v29, v16
	v_cmp_le_i32_e64 s[76:77], v29, v17
	v_or_b32_e32 v29, s78, v161
	s_and_b64 s[76:77], vcc, s[76:77]
	v_cmp_gt_i32_e32 vcc, v29, v16
	v_cmp_le_i32_e64 s[78:79], v29, v17
	s_and_b64 s[70:71], s[80:81], s[70:71]
	s_and_b64 s[74:75], s[80:81], s[74:75]
	s_and_b64 s[76:77], s[80:81], s[76:77]
	s_and_b64 s[78:79], vcc, s[78:79]
	v_cmp_ge_i32_e32 vcc, v29, v16
	v_cmp_lt_i32_e64 s[80:81], v29, v17
	v_or_b32_e32 v30, 2, v29
	s_and_b64 s[80:81], vcc, s[80:81]
	v_cmp_gt_i32_e32 vcc, v30, v16
	v_cmp_le_i32_e64 s[82:83], v30, v17
	v_or_b32_e32 v29, 3, v29
	s_and_b64 s[82:83], vcc, s[82:83]
	v_cmp_gt_i32_e32 vcc, v29, v16
	v_cmp_le_i32_e64 s[84:85], v29, v17
	v_xor_b32_e32 v17, 16, v199
	s_and_b64 s[84:85], vcc, s[84:85]
	v_cmp_lt_i32_e32 vcc, v17, v50
	s_add_u32 s88, s88, s96
	s_addc_u32 s89, s89, 0
	v_cndmask_b32_e32 v17, v199, v17, vcc
	v_lshlrev_b32_e32 v65, 2, v17
	v_xor_b32_e32 v17, 32, v199
	v_cmp_lt_i32_e32 vcc, v17, v50
	v_lshl_add_u64 v[32:33], s[88:89], 0, v[88:89]
	v_add_u32_e32 v29, 0x3600, v64
	v_cndmask_b32_e32 v17, v199, v17, vcc
	v_lshlrev_b32_e32 v66, 2, v17
	v_mov_b32_e32 v17, v99
	s_movk_i32 vcc_lo, 0x4400
	v_lshl_add_u64 v[16:17], s[88:89], 0, v[16:17]
	v_mad_u64_u32 v[34:35], s[96:97], v32, vcc_lo, v[48:49]
	v_lshlrev_b64 v[16:17], 11, v[16:17]
	v_add_u32_e32 v30, 0x4800, v64
	v_mad_i32_i24 v35, v33, vcc_lo, v35
	v_or_b32_e32 v16, s0, v16
	v_lshl_add_u64 v[56:57], v[116:117], 0, v[34:35]
	v_lshl_add_u64 v[58:59], v[118:119], 0, v[16:17]
	s_mov_b64 s[96:97], 0
	v_add_u32_e32 v67, v184, v19
	v_add_u32_e32 v68, v184, v18
	v_add_u32_e32 v69, v184, v20
	v_add_u32_e32 v70, v184, v21
	v_add_u32_e32 v71, v184, v22
	v_add_u32_e32 v72, v184, v23
	v_add_u32_e32 v73, v184, v24
	v_add_u32_e32 v74, v184, v25
	v_add_u32_e32 v75, v184, v26
	v_add_u32_e32 v76, v184, v27
	v_add_u32_e32 v77, v184, v28
	v_add_u32_e32 v78, v193, v29
	v_add_u32_e32 v79, v193, v30
	s_waitcnt vmcnt(0)
	s_branch .LBB0_406
; #define MFMA16(a, b, c) __builtin_amdgcn_mfma_f32_16x16x32_bf16((a), (b), (c), 0, 0, 0)
; #define LBAR() do { asm volatile("s_waitcnt lgkmcnt(0)" ::: "memory"); __builtin_amdgcn_s_barrier(); asm volatile("" ::: "memory"); } while (0)
; __device__ __forceinline__ void swa_compute(SwaRaw& R, int b, int kvh, int nb, const bf16_t* P, const float* __restrict__ qg, const float* __restrict__ kg, const float* __restrict__ sinks, bf16_t* OB, LAS unsigned char* lds, int tid) {
;     ...
;         LBAR();
;         f32x4 s[10];
; #pragma unroll
;         for (int j = 0; j < 10; ++j) { f32x4 acc = {0.f, 0.f, 0.f, 0.f};
; #pragma unroll
;             for (int ks = 0; ks < 2; ++ks) acc = MFMA16(ldfrag(Ks, 72, (kt0 + j) * 16 + fr, ks * 32 + 8 * fq), ldfrag(Qs, 72, wid * 16 + fr, ks * 32 + 8 * fq), acc);
;             s[j] = acc; }
;         const int qi = wid * 16 + fr; const float sink = sinks[hq]; float m = sink;
; #pragma unroll
;         for (int j = 0; j < 10; ++j)
; #pragma unroll
;             for (int r = 0; r < 4; ++r) { const int ki = (kt0 + j) * 16 + 4 * fq + r; const bool valid = (ki > qi) && (ki <= qi + 128) && ((nb > 0) || (ki >= 128));
;                 s[j][r] = valid ? s[j][r] : -INFINITY; m = fmaxf(m, s[j][r]); }
.LBB0_405:
	s_waitcnt lgkmcnt(0)
	s_barrier
	s_load_dword s99, s[2:3], 0x0
	ds_read_b128 v[16:19], v67 offset:18432
	ds_read_b128 v[80:83], v68
	ds_read_b128 v[20:23], v67 offset:18496
	ds_read_b128 v[84:87], v68 offset:64
	s_waitcnt lgkmcnt(2)
	v_mfma_f32_16x16x32_bf16 v[16:19], v[16:19], v[80:83], 0
	s_waitcnt lgkmcnt(0)
	v_mfma_f32_16x16x32_bf16 v[52:55], v[20:23], v[84:87], v[16:19]
	ds_read_b128 v[20:23], v69 offset:18496
	s_nop 4
	ds_read_b128 v[16:19], v69 offset:18432
	s_waitcnt lgkmcnt(0)
	v_mfma_f32_16x16x32_bf16 v[16:19], v[16:19], v[80:83], 0
	v_cndmask_b32_e64 v52, v201, v52, s[4:5]
	v_cndmask_b32_e64 v53, v201, v53, s[6:7]
	v_cndmask_b32_e64 v54, v201, v54, s[8:9]
	v_mfma_f32_16x16x32_bf16 v[48:51], v[20:23], v[84:87], v[16:19]
	ds_read_b128 v[20:23], v70 offset:18496
	v_cndmask_b32_e64 v55, v201, v55, s[10:11]
	s_nop 1
	ds_read_b128 v[16:19], v70 offset:18432
	s_waitcnt lgkmcnt(0)
	v_mfma_f32_16x16x32_bf16 v[16:19], v[16:19], v[80:83], 0
	s_nop 0
	v_cndmask_b32_e64 v48, v201, v48, s[12:13]
	v_cndmask_b32_e64 v49, v201, v49, s[14:15]
	v_cndmask_b32_e64 v50, v201, v50, s[16:17]
	v_mfma_f32_16x16x32_bf16 v[44:47], v[20:23], v[84:87], v[16:19]
	ds_read_b128 v[20:23], v71 offset:18496
	v_cndmask_b32_e64 v51, v201, v51, s[18:19]
	s_nop 0
	ds_read_b128 v[16:19], v71 offset:18432
	s_waitcnt lgkmcnt(0)
	v_mfma_f32_16x16x32_bf16 v[16:19], v[16:19], v[80:83], 0
	s_nop 1
	v_cndmask_b32_e64 v44, v201, v44, s[20:21]
	v_cndmask_b32_e64 v45, v201, v45, s[22:23]
	v_cndmask_b32_e64 v46, v201, v46, s[24:25]
	v_mfma_f32_16x16x32_bf16 v[40:43], v[20:23], v[84:87], v[16:19]
	ds_read_b128 v[20:23], v72 offset:18496
	v_cndmask_b32_e64 v47, v201, v47, s[26:27]
	s_nop 0
	ds_read_b128 v[16:19], v72 offset:18432
	s_waitcnt lgkmcnt(0)
	v_mfma_f32_16x16x32_bf16 v[16:19], v[16:19], v[80:83], 0
	s_nop 1
	v_cndmask_b32_e64 v40, v201, v40, s[28:29]
	v_cndmask_b32_e64 v41, v201, v41, s[30:31]
	v_cndmask_b32_e64 v42, v201, v42, s[34:35]
	v_mfma_f32_16x16x32_bf16 v[36:39], v[20:23], v[84:87], v[16:19]
	ds_read_b128 v[20:23], v73 offset:18496
	v_cndmask_b32_e64 v43, v201, v43, s[36:37]
	s_nop 0
	ds_read_b128 v[16:19], v73 offset:18432
	s_waitcnt lgkmcnt(0)
	v_mfma_f32_16x16x32_bf16 v[16:19], v[16:19], v[80:83], 0
	s_nop 1
	v_cndmask_b32_e64 v36, v201, v36, s[38:39]
	v_cndmask_b32_e64 v37, v201, v37, s[40:41]
	v_cndmask_b32_e64 v38, v201, v38, s[42:43]
	v_mfma_f32_16x16x32_bf16 v[32:35], v[20:23], v[84:87], v[16:19]
	ds_read_b128 v[20:23], v74 offset:18496
	v_cndmask_b32_e64 v39, v201, v39, s[44:45]
	s_nop 0
	ds_read_b128 v[16:19], v74 offset:18432
	s_waitcnt lgkmcnt(0)
	v_mfma_f32_16x16x32_bf16 v[16:19], v[16:19], v[80:83], 0
	s_nop 1
	v_cndmask_b32_e64 v32, v201, v32, s[46:47]
	v_cndmask_b32_e64 v33, v201, v33, s[48:49]
	v_cndmask_b32_e64 v34, v201, v34, s[50:51]
	v_mfma_f32_16x16x32_bf16 v[28:31], v[20:23], v[84:87], v[16:19]
	ds_read_b128 v[20:23], v75 offset:18496
	v_cndmask_b32_e64 v35, v201, v35, s[52:53]
	s_nop 0
	ds_read_b128 v[16:19], v75 offset:18432
	s_waitcnt lgkmcnt(0)
	v_mfma_f32_16x16x32_bf16 v[16:19], v[16:19], v[80:83], 0
	s_nop 1
	v_cndmask_b32_e64 v28, v201, v28, s[54:55]
	v_cndmask_b32_e64 v29, v201, v29, s[56:57]
	v_cndmask_b32_e64 v30, v201, v30, s[58:59]
	v_mfma_f32_16x16x32_bf16 v[24:27], v[20:23], v[84:87], v[16:19]
	ds_read_b128 v[20:23], v76 offset:18496
	v_cndmask_b32_e64 v31, v201, v31, s[60:61]
	s_nop 0
	ds_read_b128 v[16:19], v76 offset:18432
	s_waitcnt lgkmcnt(0)
	v_mfma_f32_16x16x32_bf16 v[16:19], v[16:19], v[80:83], 0
	s_nop 1
	v_cndmask_b32_e64 v24, v201, v24, s[62:63]
	v_cndmask_b32_e64 v25, v201, v25, s[64:65]
	v_cndmask_b32_e64 v26, v201, v26, s[66:67]
	v_mfma_f32_16x16x32_bf16 v[20:23], v[20:23], v[84:87], v[16:19]
	v_cndmask_b32_e64 v27, v201, v27, s[68:69]
	s_nop 1
	ds_read_b128 v[16:19], v77 offset:18432
	s_waitcnt lgkmcnt(0)
	v_mfma_f32_16x16x32_bf16 v[16:19], v[16:19], v[80:83], 0
	ds_read_b128 v[80:83], v77 offset:18496
	s_nop 0
	v_cndmask_b32_e64 v20, v201, v20, s[70:71]
	v_cndmask_b32_e64 v21, v201, v21, s[72:73]
	s_waitcnt lgkmcnt(0)
	v_mfma_f32_16x16x32_bf16 v[16:19], v[80:83], v[84:87], v[16:19]
	v_cndmask_b32_e64 v22, v201, v22, s[74:75]
	v_cndmask_b32_e64 v23, v201, v23, s[76:77]
	s_nop 4
	v_cndmask_b32_e64 v82, v201, v16, s[78:79]
	v_cndmask_b32_e64 v17, v201, v17, s[80:81]
	v_cndmask_b32_e64 v83, v201, v19, s[84:85]
	s_waitcnt lgkmcnt(0)
	v_mov_b32_e32 v80, s99
	v_max3_f32 v81, v80, v52, v53
	v_max3_f32 v81, v81, v54, v55
	v_max3_f32 v81, v81, v48, v49
	v_max3_f32 v81, v81, v50, v51
	v_max3_f32 v81, v81, v44, v45
	v_max3_f32 v81, v81, v46, v47
	v_max3_f32 v81, v81, v40, v41
	v_max3_f32 v81, v81, v42, v43
	v_max3_f32 v81, v81, v36, v37
	v_max3_f32 v81, v81, v38, v39
	v_max3_f32 v81, v81, v32, v33
	v_max3_f32 v81, v81, v34, v35
	v_max3_f32 v81, v81, v28, v29
	v_max3_f32 v81, v81, v30, v31
	v_max3_f32 v81, v81, v24, v25
	v_max3_f32 v81, v81, v26, v27
	v_max3_f32 v81, v81, v20, v21
	v_max3_f32 v81, v81, v22, v23
	v_max3_f32 v16, v81, v82, v17
	v_cndmask_b32_e64 v81, v201, v18, s[82:83]
	v_max3_f32 v16, v16, v81, v83
	ds_bpermute_b32 v18, v65, v16
	s_waitcnt lgkmcnt(0)
	v_max_f32_e32 v18, v18, v18
	v_max_f32_e32 v16, v16, v18
	ds_bpermute_b32 v18, v66, v16
	s_waitcnt lgkmcnt(0)
; __device__ __forceinline__ unsigned cvt_pk_bf16(float lo, float hi) { unsigned r; asm volatile("v_cvt_pk_bf16_f32 %0, %1, %2" : "=v"(r) : "v"(lo), "v"(hi)); return r; }
; #define LAS __attribute__((address_space(3)))
; __device__ __forceinline__ void swa_compute(SwaRaw& R, int b, int kvh, int nb, const bf16_t* P, const float* __restrict__ qg, const float* __restrict__ kg, const float* __restrict__ sinks, bf16_t* OB, LAS unsigned char* lds, int tid) {
;     ...
;         m = fmaxf(m, __shfl_xor(m, 16)); m = fmaxf(m, __shfl_xor(m, 32));
;         float sum = 0.f;
; #pragma unroll
;         for (int j = 0; j < 10; ++j) {
; #pragma unroll
;             for (int r = 0; r < 4; ++r) { s[j][r] = __expf(s[j][r] - m); sum += s[j][r]; }
;             u32x2 w; w.x = cvt_pk_bf16(s[j][0], s[j][1]); w.y = cvt_pk_bf16(s[j][2], s[j][3]);
;             *(LAS u32x2*)(Pw + fr * 168 + j * 16 + 4 * fq) = w; }
	v_max_f32_e32 v18, v18, v18
	v_max_f32_e32 v16, v16, v18
	v_sub_f32_e32 v18, v52, v16
	v_mul_f32_e32 v18, 0x3fb8aa3b, v18
	v_sub_f32_e32 v52, v53, v16
	v_exp_f32_e32 v18, v18
	v_mul_f32_e32 v52, 0x3fb8aa3b, v52
	v_sub_f32_e32 v53, v54, v16
	v_exp_f32_e32 v52, v52
	v_mul_f32_e32 v53, 0x3fb8aa3b, v53
	v_sub_f32_e32 v54, v55, v16
	v_exp_f32_e32 v53, v53
	v_mul_f32_e32 v54, 0x3fb8aa3b, v54
	v_exp_f32_e32 v54, v54
	v_add_f32_e32 v19, 0, v18
	v_add_f32_e32 v19, v52, v19
	v_add_f32_e32 v19, v53, v19
	v_cvt_pk_bf16_f32 v18, v18, v52
	v_add_f32_e32 v55, v54, v19
	v_cvt_pk_bf16_f32 v19, v53, v54
	ds_write_b64 v63, v[18:19]
	v_sub_f32_e32 v18, v48, v16
	v_mul_f32_e32 v18, 0x3fb8aa3b, v18
	v_sub_f32_e32 v48, v49, v16
	v_exp_f32_e32 v18, v18
	v_mul_f32_e32 v48, 0x3fb8aa3b, v48
	v_sub_f32_e32 v49, v50, v16
	v_exp_f32_e32 v48, v48
	v_mul_f32_e32 v49, 0x3fb8aa3b, v49
	v_sub_f32_e32 v50, v51, v16
	v_exp_f32_e32 v49, v49
	v_mul_f32_e32 v50, 0x3fb8aa3b, v50
	v_exp_f32_e32 v50, v50
	v_add_f32_e32 v19, v18, v55
	v_add_f32_e32 v19, v48, v19
	v_add_f32_e32 v19, v49, v19
	v_cvt_pk_bf16_f32 v18, v18, v48
	v_add_f32_e32 v51, v50, v19
	v_cvt_pk_bf16_f32 v19, v49, v50
	ds_write_b64 v63, v[18:19] offset:32
	v_sub_f32_e32 v18, v44, v16
	v_mul_f32_e32 v18, 0x3fb8aa3b, v18
	v_sub_f32_e32 v44, v45, v16
	v_exp_f32_e32 v18, v18
	v_mul_f32_e32 v44, 0x3fb8aa3b, v44
	v_sub_f32_e32 v45, v46, v16
	v_exp_f32_e32 v44, v44
	v_mul_f32_e32 v45, 0x3fb8aa3b, v45
	v_sub_f32_e32 v46, v47, v16
	v_exp_f32_e32 v45, v45
	v_mul_f32_e32 v46, 0x3fb8aa3b, v46
	v_exp_f32_e32 v46, v46
	v_add_f32_e32 v19, v18, v51
	v_add_f32_e32 v19, v44, v19
	v_add_f32_e32 v19, v45, v19
	v_cvt_pk_bf16_f32 v18, v18, v44
	v_add_f32_e32 v47, v46, v19
	v_cvt_pk_bf16_f32 v19, v45, v46
	ds_write_b64 v63, v[18:19] offset:64
	v_sub_f32_e32 v18, v40, v16
	v_mul_f32_e32 v18, 0x3fb8aa3b, v18
	v_sub_f32_e32 v40, v41, v16
	v_exp_f32_e32 v18, v18
	v_mul_f32_e32 v40, 0x3fb8aa3b, v40
	v_sub_f32_e32 v41, v42, v16
	v_exp_f32_e32 v40, v40
	v_mul_f32_e32 v41, 0x3fb8aa3b, v41
	v_sub_f32_e32 v42, v43, v16
	v_exp_f32_e32 v41, v41
	v_mul_f32_e32 v42, 0x3fb8aa3b, v42
	v_exp_f32_e32 v42, v42
	v_add_f32_e32 v19, v18, v47
	v_add_f32_e32 v19, v40, v19
	v_add_f32_e32 v19, v41, v19
	v_cvt_pk_bf16_f32 v18, v18, v40
	v_add_f32_e32 v43, v42, v19
	v_cvt_pk_bf16_f32 v19, v41, v42
	ds_write_b64 v63, v[18:19] offset:96
	v_sub_f32_e32 v18, v36, v16
	v_mul_f32_e32 v18, 0x3fb8aa3b, v18
	v_sub_f32_e32 v36, v37, v16
	v_exp_f32_e32 v18, v18
	v_mul_f32_e32 v36, 0x3fb8aa3b, v36
	v_sub_f32_e32 v37, v38, v16
	v_exp_f32_e32 v36, v36
	v_mul_f32_e32 v37, 0x3fb8aa3b, v37
	v_sub_f32_e32 v38, v39, v16
	v_exp_f32_e32 v37, v37
	v_mul_f32_e32 v38, 0x3fb8aa3b, v38
	v_exp_f32_e32 v38, v38
	v_add_f32_e32 v19, v18, v43
	v_add_f32_e32 v19, v36, v19
	v_add_f32_e32 v19, v37, v19
	v_cvt_pk_bf16_f32 v18, v18, v36
	v_add_f32_e32 v39, v38, v19
	v_cvt_pk_bf16_f32 v19, v37, v38
	ds_write_b64 v63, v[18:19] offset:128
	v_sub_f32_e32 v18, v32, v16
	v_mul_f32_e32 v18, 0x3fb8aa3b, v18
	v_sub_f32_e32 v32, v33, v16
	v_exp_f32_e32 v18, v18
	v_mul_f32_e32 v32, 0x3fb8aa3b, v32
	v_sub_f32_e32 v33, v34, v16
	v_exp_f32_e32 v32, v32
	v_mul_f32_e32 v33, 0x3fb8aa3b, v33
	v_sub_f32_e32 v34, v35, v16
	v_exp_f32_e32 v33, v33
	v_mul_f32_e32 v34, 0x3fb8aa3b, v34
	v_exp_f32_e32 v34, v34
	v_add_f32_e32 v19, v18, v39
	v_add_f32_e32 v19, v32, v19
	v_add_f32_e32 v19, v33, v19
	v_cvt_pk_bf16_f32 v18, v18, v32
	v_add_f32_e32 v35, v34, v19
	v_cvt_pk_bf16_f32 v19, v33, v34
	ds_write_b64 v63, v[18:19] offset:160
	v_sub_f32_e32 v18, v28, v16
	v_mul_f32_e32 v18, 0x3fb8aa3b, v18
	v_sub_f32_e32 v28, v29, v16
	v_exp_f32_e32 v18, v18
	v_mul_f32_e32 v28, 0x3fb8aa3b, v28
	v_sub_f32_e32 v29, v30, v16
	v_exp_f32_e32 v28, v28
	v_mul_f32_e32 v29, 0x3fb8aa3b, v29
	v_sub_f32_e32 v30, v31, v16
	v_exp_f32_e32 v29, v29
	v_mul_f32_e32 v30, 0x3fb8aa3b, v30
	v_exp_f32_e32 v30, v30
	v_add_f32_e32 v19, v18, v35
	v_add_f32_e32 v19, v28, v19
	v_add_f32_e32 v19, v29, v19
	v_cvt_pk_bf16_f32 v18, v18, v28
	v_add_f32_e32 v31, v30, v19
	v_cvt_pk_bf16_f32 v19, v29, v30
	ds_write_b64 v63, v[18:19] offset:192
	v_sub_f32_e32 v18, v24, v16
	v_mul_f32_e32 v18, 0x3fb8aa3b, v18
	v_sub_f32_e32 v24, v25, v16
	v_exp_f32_e32 v18, v18
	v_mul_f32_e32 v24, 0x3fb8aa3b, v24
	v_sub_f32_e32 v25, v26, v16
	v_exp_f32_e32 v24, v24
	v_mul_f32_e32 v25, 0x3fb8aa3b, v25
	v_sub_f32_e32 v26, v27, v16
	v_exp_f32_e32 v25, v25
	v_mul_f32_e32 v26, 0x3fb8aa3b, v26
	v_exp_f32_e32 v26, v26
	v_add_f32_e32 v19, v18, v31
	v_add_f32_e32 v19, v24, v19
	v_add_f32_e32 v19, v25, v19
	v_cvt_pk_bf16_f32 v18, v18, v24
	v_add_f32_e32 v27, v26, v19
	v_cvt_pk_bf16_f32 v19, v25, v26
	ds_write_b64 v63, v[18:19] offset:224
	v_sub_f32_e32 v18, v20, v16
	v_mul_f32_e32 v18, 0x3fb8aa3b, v18
	v_sub_f32_e32 v20, v21, v16
	v_exp_f32_e32 v18, v18
	v_mul_f32_e32 v20, 0x3fb8aa3b, v20
	v_sub_f32_e32 v21, v22, v16
	v_exp_f32_e32 v20, v20
	v_mul_f32_e32 v21, 0x3fb8aa3b, v21
	v_sub_f32_e32 v22, v23, v16
	v_exp_f32_e32 v21, v21
	v_mul_f32_e32 v22, 0x3fb8aa3b, v22
	v_exp_f32_e32 v22, v22
	v_add_f32_e32 v19, v18, v27
	v_add_f32_e32 v19, v20, v19
	v_add_f32_e32 v19, v21, v19
	v_cvt_pk_bf16_f32 v18, v18, v20
	v_add_f32_e32 v23, v22, v19
	v_cvt_pk_bf16_f32 v19, v21, v22
	ds_write_b64 v63, v[18:19] offset:256
	v_sub_f32_e32 v18, v82, v16
	v_mul_f32_e32 v18, 0x3fb8aa3b, v18
	v_sub_f32_e32 v17, v17, v16
	v_exp_f32_e32 v18, v18
	v_mul_f32_e32 v17, 0x3fb8aa3b, v17
	v_sub_f32_e32 v20, v81, v16
	v_exp_f32_e32 v17, v17
	v_mul_f32_e32 v20, 0x3fb8aa3b, v20
	v_sub_f32_e32 v21, v83, v16
	v_exp_f32_e32 v20, v20
	v_mul_f32_e32 v21, 0x3fb8aa3b, v21
	v_exp_f32_e32 v21, v21
	v_add_f32_e32 v19, v18, v23
	v_add_f32_e32 v19, v17, v19
	v_add_f32_e32 v19, v20, v19
	v_add_f32_e32 v22, v21, v19
	v_cvt_pk_bf16_f32 v18, v18, v17
	ds_bpermute_b32 v17, v65, v22
	v_cvt_pk_bf16_f32 v19, v20, v21
	ds_write_b64 v63, v[18:19] offset:288
	v_sub_f32_e32 v16, v80, v16
	v_mul_f32_e32 v16, 0x3fb8aa3b, v16
	s_waitcnt lgkmcnt(1)
; __device__ __forceinline__ unsigned cvt_pk_bf16(float lo, float hi) { unsigned r; asm volatile("v_cvt_pk_bf16_f32 %0, %1, %2" : "=v"(r) : "v"(lo), "v"(hi)); return r; }
; #define LAS __attribute__((address_space(3)))
; #define MFMA16(a, b, c) __builtin_amdgcn_mfma_f32_16x16x32_bf16((a), (b), (c), 0, 0, 0)
; #define LBAR() do { asm volatile("s_waitcnt lgkmcnt(0)" ::: "memory"); __builtin_amdgcn_s_barrier(); asm volatile("" ::: "memory"); } while (0)
; __device__ __forceinline__ void swa_compute(SwaRaw& R, int b, int kvh, int nb, const bf16_t* P, const float* __restrict__ qg, const float* __restrict__ kg, const float* __restrict__ sinks, bf16_t* OB, LAS unsigned char* lds, int tid) {
;     ...
;         sum += __shfl_xor(sum, 16); sum += __shfl_xor(sum, 32);
;         const float inv = 1.0f / (sum + __expf(sink - m));
;         asm volatile("s_waitcnt lgkmcnt(0)" ::: "memory"); __builtin_amdgcn_wave_barrier();
; #pragma unroll
;         for (int dt = 0; dt < 4; ++dt) { f32x4 acc = {0.f, 0.f, 0.f, 0.f};
; #pragma unroll
;             for (int ks = 0; ks < 5; ++ks) { const LAS bf16_t* vp = Vr + (kt0 * 16 + ks * 32 + 8 * fq + (fr >> 2)) * 72 + dt * 16 + 4 * (fr & 3);
;                 const v4i16_t lo = __builtin_amdgcn_ds_read_tr16_b64_v4i16((LAS v4i16_t*)vp), hi = __builtin_amdgcn_ds_read_tr16_b64_v4i16((LAS v4i16_t*)(vp + 4 * 72));
;                 const bf16x8 vf = {lo[0], lo[1], lo[2], lo[3], hi[0], hi[1], hi[2], hi[3]};
;                 acc = MFMA16(vf, ldfrag(Pw, 168, fr, ks * 32 + 8 * fq), acc); }
;             u32x2 w; w.x = cvt_pk_bf16(acc[0] * inv, acc[1] * inv); w.y = cvt_pk_bf16(acc[2] * inv, acc[3] * inv);
;             *(u32x2*)(OB + (rq0 + qi) * 1024 + hq * 64 + dt * 16 + 4 * fq) = w; }
;         LBAR();
	v_add_f32_e32 v17, v22, v17
	ds_bpermute_b32 v18, v66, v17
	v_exp_f32_e32 v16, v16
	v_add_u32_e32 v31, v193, v64
	v_add_u32_e32 v32, v63, v94
	s_waitcnt lgkmcnt(0)
	s_waitcnt lgkmcnt(0)
	v_add_f32_e32 v17, v17, v18
	v_add_f32_e32 v16, v16, v17
	v_div_scale_f32 v17, s[88:89], v16, v16, 1.0
	v_rcp_f32_e32 v18, v17
	s_nop 0
	v_fma_f32 v19, -v17, v18, 1.0
	v_fmac_f32_e32 v18, v19, v18
	v_div_scale_f32 v19, vcc, 1.0, v16, 1.0
	v_mul_f32_e32 v20, v19, v18
	v_fma_f32 v21, -v17, v20, v19
	v_fmac_f32_e32 v20, v21, v18
	v_fma_f32 v17, -v17, v20, v19
	v_div_fmas_f32 v17, v17, v18, v20
	ds_read_b64_tr_b16 v[18:19], v31 offset:55296
	ds_read_b64_tr_b16 v[20:21], v31 offset:55872
	ds_read_b128 v[22:25], v32
	s_waitcnt lgkmcnt(0)
	v_mfma_f32_16x16x32_bf16 v[18:21], v[18:21], v[22:25], 0
	ds_read_b64_tr_b16 v[22:23], v31 offset:59904
	ds_read_b64_tr_b16 v[24:25], v31 offset:60480
	ds_read_b128 v[26:29], v32 offset:64
	v_div_fixup_f32 v30, v17, v16, 1.0
	v_lshl_add_u64 v[16:17], v[58:59], 0, s[96:97]
	s_waitcnt lgkmcnt(0)
	v_mfma_f32_16x16x32_bf16 v[18:21], v[22:25], v[26:29], v[18:21]
	ds_read_b64_tr_b16 v[22:23], v31 offset:64512
	ds_read_b64_tr_b16 v[24:25], v31 offset:65088
	ds_read_b128 v[26:29], v32 offset:128
	s_add_u32 s96, s96, 0x80
	s_addc_u32 s97, s97, 0
	s_waitcnt lgkmcnt(0)
	v_mfma_f32_16x16x32_bf16 v[18:21], v[22:25], v[26:29], v[18:21]
	ds_read_b64_tr_b16 v[22:23], v78 offset:55296
	ds_read_b64_tr_b16 v[24:25], v78 offset:55872
	ds_read_b128 v[26:29], v32 offset:192
	s_add_u32 s2, s2, 4
	s_addc_u32 s3, s3, 0
	s_waitcnt lgkmcnt(0)
	v_mfma_f32_16x16x32_bf16 v[18:21], v[22:25], v[26:29], v[18:21]
	ds_read_b64_tr_b16 v[22:23], v79 offset:55296
	ds_read_b64_tr_b16 v[24:25], v79 offset:55872
	ds_read_b128 v[26:29], v32 offset:256
	s_cmpk_lg_i32 s96, 0x200
	s_waitcnt lgkmcnt(0)
	v_mfma_f32_16x16x32_bf16 v[18:21], v[22:25], v[26:29], v[18:21]
	s_nop 7
	v_mul_f32_e32 v18, v18, v30
	v_mul_f32_e32 v19, v19, v30
	v_cvt_pk_bf16_f32 v18, v18, v19
	v_mul_f32_e32 v19, v20, v30
	v_mul_f32_e32 v20, v21, v30
	v_cvt_pk_bf16_f32 v19, v19, v20
	global_store_dwordx2 v[16:17], v[18:19], off offset:-64
	ds_read_b64_tr_b16 v[18:19], v31 offset:55328
	ds_read_b64_tr_b16 v[20:21], v31 offset:55904
	ds_read_b128 v[22:25], v32
	s_waitcnt lgkmcnt(0)
	v_mfma_f32_16x16x32_bf16 v[18:21], v[18:21], v[22:25], 0
	ds_read_b64_tr_b16 v[22:23], v31 offset:59936
	ds_read_b64_tr_b16 v[24:25], v31 offset:60512
	ds_read_b128 v[26:29], v32 offset:64
	s_waitcnt lgkmcnt(0)
	v_mfma_f32_16x16x32_bf16 v[18:21], v[22:25], v[26:29], v[18:21]
	ds_read_b64_tr_b16 v[22:23], v31 offset:64544
	ds_read_b64_tr_b16 v[24:25], v31 offset:65120
	ds_read_b128 v[26:29], v32 offset:128
	s_waitcnt lgkmcnt(0)
	v_mfma_f32_16x16x32_bf16 v[18:21], v[22:25], v[26:29], v[18:21]
	ds_read_b64_tr_b16 v[22:23], v78 offset:55328
	ds_read_b64_tr_b16 v[24:25], v78 offset:55904
	ds_read_b128 v[26:29], v32 offset:192
	s_waitcnt lgkmcnt(0)
	v_mfma_f32_16x16x32_bf16 v[18:21], v[22:25], v[26:29], v[18:21]
	ds_read_b64_tr_b16 v[22:23], v79 offset:55328
	ds_read_b64_tr_b16 v[24:25], v79 offset:55904
	ds_read_b128 v[26:29], v32 offset:256
	s_waitcnt lgkmcnt(0)
	v_mfma_f32_16x16x32_bf16 v[18:21], v[22:25], v[26:29], v[18:21]
	s_nop 7
	v_mul_f32_e32 v18, v18, v30
	v_mul_f32_e32 v19, v19, v30
	v_cvt_pk_bf16_f32 v18, v18, v19
	v_mul_f32_e32 v19, v20, v30
	v_mul_f32_e32 v20, v21, v30
	v_cvt_pk_bf16_f32 v19, v19, v20
	global_store_dwordx2 v[16:17], v[18:19], off offset:-32
	ds_read_b64_tr_b16 v[18:19], v31 offset:55360
	ds_read_b64_tr_b16 v[20:21], v31 offset:55936
	ds_read_b128 v[22:25], v32
	s_waitcnt lgkmcnt(0)
	v_mfma_f32_16x16x32_bf16 v[18:21], v[18:21], v[22:25], 0
	ds_read_b64_tr_b16 v[22:23], v31 offset:59968
	ds_read_b64_tr_b16 v[24:25], v31 offset:60544
	ds_read_b128 v[26:29], v32 offset:64
	s_waitcnt lgkmcnt(0)
	v_mfma_f32_16x16x32_bf16 v[18:21], v[22:25], v[26:29], v[18:21]
	ds_read_b64_tr_b16 v[22:23], v31 offset:64576
	ds_read_b64_tr_b16 v[24:25], v31 offset:65152
	ds_read_b128 v[26:29], v32 offset:128
	s_waitcnt lgkmcnt(0)
	v_mfma_f32_16x16x32_bf16 v[18:21], v[22:25], v[26:29], v[18:21]
	ds_read_b64_tr_b16 v[22:23], v78 offset:55360
	ds_read_b64_tr_b16 v[24:25], v78 offset:55936
	ds_read_b128 v[26:29], v32 offset:192
	s_waitcnt lgkmcnt(0)
	v_mfma_f32_16x16x32_bf16 v[18:21], v[22:25], v[26:29], v[18:21]
	ds_read_b64_tr_b16 v[22:23], v79 offset:55360
	ds_read_b64_tr_b16 v[24:25], v79 offset:55936
	ds_read_b128 v[26:29], v32 offset:256
	s_waitcnt lgkmcnt(0)
	v_mfma_f32_16x16x32_bf16 v[18:21], v[22:25], v[26:29], v[18:21]
	s_nop 7
	v_mul_f32_e32 v18, v30, v18
	v_mul_f32_e32 v19, v30, v19
	v_cvt_pk_bf16_f32 v18, v18, v19
	v_mul_f32_e32 v19, v30, v20
	v_mul_f32_e32 v20, v30, v21
	v_cvt_pk_bf16_f32 v19, v19, v20
	global_store_dwordx2 v[16:17], v[18:19], off
	ds_read_b64_tr_b16 v[18:19], v31 offset:55392
	ds_read_b64_tr_b16 v[20:21], v31 offset:55968
	ds_read_b128 v[22:25], v32
	s_waitcnt lgkmcnt(0)
	v_mfma_f32_16x16x32_bf16 v[18:21], v[18:21], v[22:25], 0
	ds_read_b64_tr_b16 v[22:23], v31 offset:60000
	ds_read_b64_tr_b16 v[24:25], v31 offset:60576
	ds_read_b128 v[26:29], v32 offset:64
	s_waitcnt lgkmcnt(0)
	v_mfma_f32_16x16x32_bf16 v[18:21], v[22:25], v[26:29], v[18:21]
	ds_read_b64_tr_b16 v[22:23], v31 offset:64608
	ds_read_b64_tr_b16 v[24:25], v31 offset:65184
	ds_read_b128 v[26:29], v32 offset:128
	s_waitcnt lgkmcnt(0)
	v_mfma_f32_16x16x32_bf16 v[18:21], v[22:25], v[26:29], v[18:21]
	ds_read_b64_tr_b16 v[22:23], v78 offset:55392
	ds_read_b64_tr_b16 v[24:25], v78 offset:55968
	ds_read_b128 v[26:29], v32 offset:192
	s_waitcnt lgkmcnt(0)
	v_mfma_f32_16x16x32_bf16 v[18:21], v[22:25], v[26:29], v[18:21]
	ds_read_b64_tr_b16 v[22:23], v79 offset:55392
	ds_read_b64_tr_b16 v[24:25], v79 offset:55968
	ds_read_b128 v[26:29], v32 offset:256
	s_waitcnt lgkmcnt(0)
	v_mfma_f32_16x16x32_bf16 v[18:21], v[22:25], v[26:29], v[18:21]
	s_nop 7
	v_mul_f32_e32 v18, v30, v18
	v_mul_f32_e32 v19, v30, v19
	v_cvt_pk_bf16_f32 v18, v18, v19
	v_mul_f32_e32 v19, v30, v20
	v_mul_f32_e32 v20, v30, v21
	v_cvt_pk_bf16_f32 v19, v19, v20
	global_store_dwordx2 v[16:17], v[18:19], off offset:32
	s_waitcnt lgkmcnt(0)
	s_barrier
	s_cbranch_scc0 .LBB0_392
; __device__ __forceinline__ unsigned cvt_pk_bf16(float lo, float hi) { unsigned r; asm volatile("v_cvt_pk_bf16_f32 %0, %1, %2" : "=v"(r) : "v"(lo), "v"(hi)); return r; }
; __device__ __forceinline__ float bflo(unsigned w) { return __uint_as_float(w << 16); }
; __device__ __forceinline__ float bfhi(unsigned w) { return __uint_as_float(w & 0xffff0000u); }
; #define LAS __attribute__((address_space(3)))
; __device__ __forceinline__ void swa_compute(SwaRaw& R, int b, int kvh, int nb, const bf16_t* P, const float* __restrict__ qg, const float* __restrict__ kg, const float* __restrict__ sinks, bf16_t* OB, LAS unsigned char* lds, int tid) {
;     ...
;         for (int p = 0; p < 2; ++p) { const int row = (tid >> 3) + 64 * p; const u32x4 raw = R.q[p];
;             float x[8] = {bflo(raw.x), bfhi(raw.x), bflo(raw.y), bfhi(raw.y), bflo(raw.z), bfhi(raw.z), bflo(raw.w), bfhi(raw.w)};
;             float ss = 0.f;
; #pragma unroll
;             for (int e = 0; e < 8; ++e) ss += x[e] * x[e];
;             ss += __shfl_xor(ss, 1); ss += __shfl_xor(ss, 2); ss += __shfl_xor(ss, 4);
;             const float rs = 0.125f / sqrtf(ss * (1.0f / 64.0f) + EPS);
;             u32x4 w; w.x = cvt_pk_bf16(x[0] * rs * qg0.x, x[1] * rs * qg0.y); w.y = cvt_pk_bf16(x[2] * rs * qg0.z, x[3] * rs * qg0.w); w.z = cvt_pk_bf16(x[4] * rs * qg1.x, x[5] * rs * qg1.y); w.w = cvt_pk_bf16(x[6] * rs * qg1.z, x[7] * rs * qg1.w);
;             *(LAS u32x4*)(Qs + row * 72 + ch * 8) = w; }
;         if (g < 3) {
; #pragma unroll
;             for (int p = 0; p < 2; ++p) R.q[p] = *(const u32x4*)(P + (rq0 + (tid >> 3) + 64 * p) * PLD + 3072 + (hq + 1) * 64 + ch * 8);
.LBB0_406:
	s_waitcnt vmcnt(4)
	v_and_b32_e32 v19, 0xffff0000, v0
	v_lshlrev_b32_e32 v18, 16, v0
	v_mul_f32_e32 v26, v19, v19
	v_lshlrev_b32_e32 v22, 16, v1
	v_fmac_f32_e32 v26, v18, v18
	v_and_b32_e32 v23, 0xffff0000, v1
	v_fmac_f32_e32 v26, v22, v22
	v_lshlrev_b32_e32 v24, 16, v2
	v_fmac_f32_e32 v26, v23, v23
	v_and_b32_e32 v25, 0xffff0000, v2
	v_fmac_f32_e32 v26, v24, v24
	v_and_b32_e32 v20, 0xffff0000, v3
	v_lshlrev_b32_e32 v21, 16, v3
	v_fmac_f32_e32 v26, v25, v25
	v_pk_mul_f32 v[16:17], v[20:21], v[20:21]
	s_cmpk_eq_i32 s96, 0x180
	v_add_f32_e32 v17, v17, v26
	v_add_f32_e32 v16, v16, v17
	ds_bpermute_b32 v17, v60, v16
	s_waitcnt lgkmcnt(0)
	v_add_f32_e32 v16, v16, v17
	ds_bpermute_b32 v17, v61, v16
	s_waitcnt lgkmcnt(0)
	v_add_f32_e32 v16, v16, v17
	ds_bpermute_b32 v17, v62, v16
	s_waitcnt lgkmcnt(0)
	v_add_f32_e32 v16, v16, v17
	v_fmamk_f32 v16, v16, 0x3c800000, v196
	v_cmp_gt_f32_e32 vcc, s90, v16
	v_mul_f32_e32 v17, 0x4f800000, v16
	s_nop 0
	v_cndmask_b32_e32 v16, v16, v17, vcc
	v_sqrt_f32_e32 v17, v16
	s_nop 0
	v_add_u32_e32 v26, -1, v17
	v_fma_f32 v27, -v26, v17, v16
	v_cmp_ge_f32_e64 s[88:89], 0, v27
	v_add_u32_e32 v27, 1, v17
	s_nop 0
	v_cndmask_b32_e64 v26, v17, v26, s[88:89]
	v_fma_f32 v17, -v27, v17, v16
	v_cmp_lt_f32_e64 s[88:89], 0, v17
	s_nop 1
	v_cndmask_b32_e64 v17, v26, v27, s[88:89]
	v_mul_f32_e32 v26, 0x37800000, v17
	v_cndmask_b32_e32 v17, v17, v26, vcc
	v_cmp_class_f32_e32 vcc, v16, v197
	s_nop 1
	v_cndmask_b32_e32 v16, v17, v16, vcc
	v_div_scale_f32 v17, s[88:89], v16, v16, s87
	v_rcp_f32_e32 v26, v17
	s_nop 0
	v_fma_f32 v27, -v17, v26, 1.0
	v_fmac_f32_e32 v26, v27, v26
	v_div_scale_f32 v27, vcc, s87, v16, s87
	v_mul_f32_e32 v28, v27, v26
	v_fma_f32 v29, -v17, v28, v27
	v_fmac_f32_e32 v28, v29, v26
	v_fma_f32 v17, -v17, v28, v27
	v_div_fmas_f32 v17, v17, v26, v28
	v_div_fixup_f32 v26, v17, v16, s87
	v_mul_f32_e32 v16, v26, v18
	v_mul_f32_e32 v17, v26, v19
	v_mul_f32_e32 v16, v8, v16
	v_mul_f32_e32 v17, v9, v17
	v_cvt_pk_bf16_f32 v16, v16, v17
	v_mul_f32_e32 v17, v26, v22
	v_mul_f32_e32 v18, v26, v23
	v_mul_f32_e32 v17, v10, v17
	v_mul_f32_e32 v18, v11, v18
	v_cvt_pk_bf16_f32 v17, v17, v18
	v_mul_f32_e32 v18, v26, v24
	v_mul_f32_e32 v19, v26, v25
	v_mul_f32_e32 v18, v12, v18
	v_mul_f32_e32 v19, v13, v19
	v_cvt_pk_bf16_f32 v18, v18, v19
	v_mul_f32_e32 v19, v26, v21
	v_mul_f32_e32 v19, v14, v19
	v_mul_f32_e32 v20, v26, v20
	v_mul_f32_e32 v20, v15, v20
	v_cvt_pk_bf16_f32 v19, v19, v20
	ds_write_b128 v198, v[16:19]
	v_and_b32_e32 v19, 0xffff0000, v4
	v_lshlrev_b32_e32 v18, 16, v4
	v_mul_f32_e32 v26, v19, v19
	v_lshlrev_b32_e32 v22, 16, v5
	v_fmac_f32_e32 v26, v18, v18
	v_and_b32_e32 v23, 0xffff0000, v5
	v_fmac_f32_e32 v26, v22, v22
	v_lshlrev_b32_e32 v24, 16, v6
	v_fmac_f32_e32 v26, v23, v23
	v_and_b32_e32 v25, 0xffff0000, v6
	v_fmac_f32_e32 v26, v24, v24
	v_and_b32_e32 v20, 0xffff0000, v7
	v_lshlrev_b32_e32 v21, 16, v7
	v_fmac_f32_e32 v26, v25, v25
	v_pk_mul_f32 v[16:17], v[20:21], v[20:21]
	s_nop 0
	v_add_f32_e32 v17, v17, v26
	v_add_f32_e32 v16, v16, v17
	ds_bpermute_b32 v17, v60, v16
	s_waitcnt lgkmcnt(0)
	v_add_f32_e32 v16, v16, v17
	ds_bpermute_b32 v17, v61, v16
	s_waitcnt lgkmcnt(0)
	v_add_f32_e32 v16, v16, v17
	ds_bpermute_b32 v17, v62, v16
	s_waitcnt lgkmcnt(0)
	v_add_f32_e32 v16, v16, v17
	v_fmamk_f32 v16, v16, 0x3c800000, v196
	v_cmp_gt_f32_e32 vcc, s90, v16
	v_mul_f32_e32 v17, 0x4f800000, v16
	s_nop 0
	v_cndmask_b32_e32 v16, v16, v17, vcc
	v_sqrt_f32_e32 v17, v16
	s_nop 0
	v_add_u32_e32 v26, -1, v17
	v_fma_f32 v27, -v26, v17, v16
	v_cmp_ge_f32_e64 s[88:89], 0, v27
	v_add_u32_e32 v27, 1, v17
	s_nop 0
	v_cndmask_b32_e64 v26, v17, v26, s[88:89]
	v_fma_f32 v17, -v27, v17, v16
	v_cmp_lt_f32_e64 s[88:89], 0, v17
	s_nop 1
	v_cndmask_b32_e64 v17, v26, v27, s[88:89]
	v_mul_f32_e32 v26, 0x37800000, v17
	v_cndmask_b32_e32 v17, v17, v26, vcc
	v_cmp_class_f32_e32 vcc, v16, v197
	s_nop 1
	v_cndmask_b32_e32 v16, v17, v16, vcc
	v_div_scale_f32 v17, s[88:89], v16, v16, s87
	v_rcp_f32_e32 v26, v17
	s_nop 0
	v_fma_f32 v27, -v17, v26, 1.0
	v_fmac_f32_e32 v26, v27, v26
	v_div_scale_f32 v27, vcc, s87, v16, s87
	v_mul_f32_e32 v28, v27, v26
	v_fma_f32 v29, -v17, v28, v27
	v_fmac_f32_e32 v28, v29, v26
	v_fma_f32 v17, -v17, v28, v27
	v_div_fmas_f32 v17, v17, v26, v28
	v_div_fixup_f32 v26, v17, v16, s87
	v_mul_f32_e32 v16, v26, v18
	v_mul_f32_e32 v17, v26, v19
	v_mul_f32_e32 v16, v8, v16
	v_mul_f32_e32 v17, v9, v17
	v_cvt_pk_bf16_f32 v16, v16, v17
	v_mul_f32_e32 v17, v26, v22
	v_mul_f32_e32 v18, v26, v23
	v_mul_f32_e32 v17, v10, v17
	v_mul_f32_e32 v18, v11, v18
	v_cvt_pk_bf16_f32 v17, v17, v18
	v_mul_f32_e32 v18, v26, v24
	v_mul_f32_e32 v19, v26, v25
	v_mul_f32_e32 v18, v12, v18
	v_mul_f32_e32 v19, v13, v19
	v_cvt_pk_bf16_f32 v18, v18, v19
	v_mul_f32_e32 v19, v26, v21
	v_mul_f32_e32 v19, v14, v19
	v_mul_f32_e32 v20, v26, v20
	v_mul_f32_e32 v20, v15, v20
	v_cvt_pk_bf16_f32 v19, v19, v20
	ds_write_b128 v198, v[16:19] offset:9216
	s_cbranch_scc1 .LBB0_405
	v_lshl_add_u64 v[0:1], v[56:57], 0, s[96:97]
	v_add_co_u32_e32 v2, vcc, 0xb801000, v0
	s_nop 1
	v_addc_co_u32_e32 v3, vcc, 0, v1, vcc
	v_add_co_u32_e32 v4, vcc, 0xb911000, v0
	s_nop 1
	v_addc_co_u32_e32 v5, vcc, 0, v1, vcc
	global_load_dwordx4 v[0:3], v[2:3], off offset:2176
	s_nop 0
	global_load_dwordx4 v[4:7], v[4:5], off offset:2176
	s_branch .LBB0_405

; __device__ __forceinline__ void swa_load(SwaRaw& R, int b, int kvh, int nb, const bf16_t* P, int tid) {
;     const size_t rq0 = (size_t)b * SEQ + (size_t)nb * 128; const int ch = tid & 7;
; #pragma unroll
;     for (int p = 0; p < 4; ++p) { const int ki = (tid >> 3) + 64 * p; const bool valid = (nb > 0) || (ki >= 128);
;         R.k[p] = (u32x4){0u, 0u, 0u, 0u}; R.v[p] = (u32x4){0u, 0u, 0u, 0u};
;         if (valid) { const size_t row = rq0 - 128 + ki; R.k[p] = *(const u32x4*)(P + row * PLD + 4096 + kvh * 64 + ch * 8); R.v[p] = *(const u32x4*)(P + row * PLD + 4352 + kvh * 64 + ch * 8); } }
; #pragma unroll
;     for (int p = 0; p < 2; ++p) R.q[p] = *(const u32x4*)(P + (rq0 + (tid >> 3) + 64 * p) * PLD + 3072 + (kvh * 4) * 64 + ch * 8);
; }
; __device__ __forceinline__ void swa_compute(SwaRaw& R, int b, int kvh, int nb, const bf16_t* P, const float* __restrict__ qg, const float* __restrict__ kg, const float* __restrict__ sinks, bf16_t* OB, LAS unsigned char* lds, int tid) {
;     const int lane = tid & 63, wid = __builtin_amdgcn_readfirstlane(tid >> 6), fr = lane & 15, fq = lane >> 4;
;     LAS bf16_t* Qs = (LAS bf16_t*)lds;
;     LAS bf16_t* Ks = Qs + 128 * 72;
;     LAS bf16_t* Vr = Ks + 256 * 72;
;     LAS bf16_t* Pw = Vr + 256 * 72 + wid * (16 * 168);
;     const size_t rq0 = (size_t)b * SEQ + (size_t)nb * 128;
;     const int ch = tid & 7;
;     {
;         const f32x4 g0 = *(const f32x4*)(kg + ch * 8), g1 = *(const f32x4*)(kg + ch * 8 + 4);
; #pragma unroll
;         for (int p = 0; p < 4; ++p) { const int ki = (tid >> 3) + 64 * p; const u32x4 raw = R.k[p], rv = R.v[p];
;             float x[8] = {bflo(raw.x), bfhi(raw.x), bflo(raw.y), bfhi(raw.y), bflo(raw.z), bfhi(raw.z), bflo(raw.w), bfhi(raw.w)};
;             float ss = 0.f;
; #pragma unroll
;             for (int e = 0; e < 8; ++e) ss += x[e] * x[e];
;             ss += __shfl_xor(ss, 1); ss += __shfl_xor(ss, 2); ss += __shfl_xor(ss, 4);
;             const float rs = 1.0f / sqrtf(ss * (1.0f / 64.0f) + EPS);
;             u32x4 w; w.x = cvt_pk_bf16(x[0] * rs * g0.x, x[1] * rs * g0.y); w.y = cvt_pk_bf16(x[2] * rs * g0.z, x[3] * rs * g0.w); w.z = cvt_pk_bf16(x[4] * rs * g1.x, x[5] * rs * g1.y); w.w = cvt_pk_bf16(x[6] * rs * g1.z, x[7] * rs * g1.w);
;             *(LAS u32x4*)(Ks + ki * 72 + ch * 8) = w;
;             *(LAS u32x4*)(Vr + ki * 72 + ch * 8) = rv; }
.LBB0_497:
	s_or_b64 exec, exec, s[2:3]
	v_readlane_b32 s12, v236, 23
	s_lshr_b32 s2, s92, 1
	v_readlane_b32 s13, v236, 24
	v_readlane_b32 s16, v236, 27
	v_readlane_b32 s17, v236, 28
	s_and_b32 s2, s2, 48
	s_mov_b64 s[12:13], s[16:17]
	s_add_u32 s2, s12, s2
	s_addc_u32 s3, s13, 0
	s_and_b32 s6, s94, 31
	s_lshl_b32 s89, s6, 7
	s_lshl_b32 s6, s92, 4
	v_lshl_add_u64 v[2:3], s[4:5], 0, v[104:105]
	v_mov_b64_e32 v[4:5], s[72:73]
	s_and_b32 s88, s6, 0x600
	v_mad_u64_u32 v[6:7], s[6:7], v2, s58, v[4:5]
	v_mov_b32_e32 v2, v7
	v_mad_u64_u32 v[2:3], s[6:7], v3, s58, v[2:3]
	v_mov_b32_e32 v7, v2
	s_lshl_b32 s96, s11, 1
	v_mov_b32_e32 v121, v1
	v_lshl_add_u64 v[2:3], v[6:7], 0, s[96:97]
	v_lshl_add_u64 v[2:3], v[2:3], 0, v[120:121]
	s_movk_i32 s6, 0x2000
	v_add_co_u32_e32 v2, vcc, s6, v2
	v_xor_b32_e32 v50, 1, v175
	s_nop 0
	v_addc_co_u32_e32 v3, vcc, 0, v3, vcc
	global_load_dwordx4 v[30:33], v[2:3], off
	global_load_dwordx4 v[26:29], v[2:3], off offset:512
	v_lshl_add_u64 v[2:3], s[4:5], 0, v[106:107]
	v_mad_u64_u32 v[6:7], s[4:5], v2, s58, v[4:5]
	v_mov_b32_e32 v2, v7
	v_mad_u64_u32 v[2:3], s[4:5], v3, s58, v[2:3]
	v_mov_b32_e32 v7, v2
	v_lshl_add_u64 v[2:3], v[6:7], 0, s[96:97]
	v_lshl_add_u64 v[2:3], v[2:3], 0, v[120:121]
	v_add_co_u32_e32 v2, vcc, s6, v2
	s_mul_i32 s6, s10, 0x4400
	s_nop 0
	v_addc_co_u32_e32 v3, vcc, 0, v3, vcc
	global_load_dwordx4 v[22:25], v[2:3], off
	global_load_dwordx4 v[10:13], v[2:3], off offset:512
	v_or_b32_e32 v2, s9, v88
	v_mad_u64_u32 v[2:3], s[4:5], v2, s58, v[4:5]
	v_add_u32_e32 v3, s6, v3
	s_lshl_b32 s96, s8, 9
	v_lshl_add_u64 v[2:3], v[2:3], 0, s[96:97]
	v_lshl_add_u64 v[6:7], v[2:3], 0, v[120:121]
	s_movk_i32 s4, 0x1000
	v_add_co_u32_e32 v2, vcc, s4, v6
	s_mov_b32 s4, 0x111000
	s_nop 0
	v_addc_co_u32_e32 v3, vcc, 0, v7, vcc
	v_add_co_u32_e32 v6, vcc, s4, v6
	global_load_dwordx4 v[2:5], v[2:3], off offset:2048
	s_nop 0
	v_addc_co_u32_e32 v7, vcc, 0, v7, vcc
	global_load_dwordx4 v[6:9], v[6:7], off offset:2048
	s_nop 0
	global_load_dwordx4 v[14:17], v[108:109], off offset:16
	global_load_dwordx4 v[18:21], v[108:109], off
	v_cmp_lt_i32_e32 vcc, v50, v76
	s_waitcnt vmcnt(9)
	v_and_b32_e32 v53, 0xffff0000, v46
	v_lshlrev_b32_e32 v52, 16, v46
	v_cndmask_b32_e32 v50, v175, v50, vcc
	v_lshlrev_b32_e32 v62, 2, v50
	v_xor_b32_e32 v50, 2, v175
	v_cmp_lt_i32_e32 vcc, v50, v76
	v_mul_f32_e32 v57, v53, v53
	v_lshlrev_b32_e32 v54, 16, v47
	v_cndmask_b32_e32 v50, v175, v50, vcc
	v_lshlrev_b32_e32 v63, 2, v50
	v_xor_b32_e32 v50, 4, v175
	v_fmac_f32_e32 v57, v52, v52
	v_cmp_lt_i32_e32 vcc, v50, v76
	v_and_b32_e32 v55, 0xffff0000, v47
	v_fmac_f32_e32 v57, v54, v54
	v_cndmask_b32_e32 v50, v175, v50, vcc
	v_lshlrev_b32_e32 v56, 16, v48
	v_fmac_f32_e32 v57, v55, v55
	v_lshlrev_b32_e32 v64, 2, v50
	v_and_b32_e32 v48, 0xffff0000, v48
	v_fmac_f32_e32 v57, v56, v56
	v_and_b32_e32 v50, 0xffff0000, v49
	v_lshlrev_b32_e32 v51, 16, v49
	v_fmac_f32_e32 v57, v48, v48
	v_pk_mul_f32 v[46:47], v[50:51], v[50:51]
	v_readfirstlane_b32 s6, v186
	v_add_f32_e32 v47, v47, v57
	v_add_f32_e32 v46, v46, v47
	ds_bpermute_b32 v47, v62, v46
	s_lshr_b32 s8, s6, 6
	v_readlane_b32 s14, v236, 25
	v_readlane_b32 s24, v236, 35
	s_mul_i32 s7, s8, 0x1500
	s_waitcnt lgkmcnt(0)
	v_add_f32_e32 v46, v46, v47
	ds_bpermute_b32 v47, v63, v46
	v_add_u32_e32 v65, s7, v171
	s_movk_i32 s14, 0x7f
	s_movk_i32 s76, 0x7e
	v_readlane_b32 s15, v236, 26
	s_waitcnt lgkmcnt(0)
	v_add_f32_e32 v46, v46, v47
	ds_bpermute_b32 v47, v64, v46
	v_readlane_b32 s22, v236, 33
	v_readlane_b32 s23, v236, 34
	v_readlane_b32 s18, v236, 29
	v_readlane_b32 s19, v236, 30
	s_waitcnt lgkmcnt(0)
	v_add_f32_e32 v46, v46, v47
	v_fmamk_f32 v46, v46, 0x3c800000, v95
	v_cmp_gt_f32_e32 vcc, s91, v46
	v_mul_f32_e32 v47, 0x4f800000, v46
	v_readlane_b32 s20, v236, 31
	v_cndmask_b32_e32 v46, v46, v47, vcc
	v_sqrt_f32_e32 v47, v46
	v_readlane_b32 s21, v236, 32
	v_readlane_b32 s25, v236, 36
	v_readlane_b32 s26, v236, 37
	v_add_u32_e32 v49, -1, v47
	v_fma_f32 v57, -v49, v47, v46
	v_cmp_ge_f32_e64 s[4:5], 0, v57
	v_add_u32_e32 v57, 1, v47
	v_readlane_b32 s27, v236, 38
	v_cndmask_b32_e64 v49, v47, v49, s[4:5]
	v_fma_f32 v47, -v57, v47, v46
	v_cmp_lt_f32_e64 s[4:5], 0, v47
	v_mov_b32_e32 v0, s88
	s_movk_i32 s96, 0x4400
	v_cndmask_b32_e64 v47, v49, v57, s[4:5]
	v_mul_f32_e32 v49, 0x37800000, v47
	v_cndmask_b32_e32 v47, v47, v49, vcc
	v_cmp_class_f32_e32 vcc, v46, v172
	s_nop 1
	v_cndmask_b32_e32 v46, v47, v46, vcc
	v_div_scale_f32 v47, s[4:5], v46, v46, 1.0
	v_rcp_f32_e32 v49, v47
	s_nop 0
	v_fma_f32 v57, -v47, v49, 1.0
	v_fmac_f32_e32 v49, v57, v49
	v_div_scale_f32 v57, vcc, 1.0, v46, 1.0
	v_mul_f32_e32 v58, v57, v49
	v_fma_f32 v59, -v47, v58, v57
	v_fmac_f32_e32 v58, v59, v49
	v_fma_f32 v47, -v47, v58, v57
	v_div_fmas_f32 v47, v47, v49, v58
	v_div_fixup_f32 v49, v47, v46, 1.0
	v_mul_f32_e32 v46, v49, v52
	v_mul_f32_e32 v47, v49, v53
	s_waitcnt vmcnt(0)
	v_mul_f32_e32 v46, v18, v46
	v_mul_f32_e32 v47, v19, v47
	v_cvt_pk_bf16_f32 v46, v46, v47
	v_mul_f32_e32 v47, v49, v54
	v_mul_f32_e32 v52, v49, v55
	v_mul_f32_e32 v47, v20, v47
	v_mul_f32_e32 v52, v21, v52
	v_cvt_pk_bf16_f32 v47, v47, v52
	v_mul_f32_e32 v52, v49, v56
	v_mul_f32_e32 v48, v49, v48
	v_mul_f32_e32 v51, v49, v51
	v_mul_f32_e32 v49, v49, v50
	v_mul_f32_e32 v48, v15, v48
	v_mul_f32_e32 v49, v17, v49
	v_mul_f32_e32 v52, v14, v52
	v_cvt_pk_bf16_f32 v48, v52, v48
	v_mul_f32_e32 v51, v16, v51
	v_cvt_pk_bf16_f32 v49, v51, v49
	ds_write_b128 v162, v[46:49] offset:18432
	ds_write_b128 v162, v[42:45] offset:55296
	v_and_b32_e32 v45, 0xffff0000, v38
	v_lshlrev_b32_e32 v44, 16, v38
	v_mul_f32_e32 v49, v45, v45
	v_lshlrev_b32_e32 v46, 16, v39
	v_fmac_f32_e32 v49, v44, v44
	v_and_b32_e32 v47, 0xffff0000, v39
	v_fmac_f32_e32 v49, v46, v46
	v_lshlrev_b32_e32 v48, 16, v40
	v_fmac_f32_e32 v49, v47, v47
	v_and_b32_e32 v40, 0xffff0000, v40
	v_fmac_f32_e32 v49, v48, v48
	v_and_b32_e32 v42, 0xffff0000, v41
	v_lshlrev_b32_e32 v43, 16, v41
	v_fmac_f32_e32 v49, v40, v40
	v_pk_mul_f32 v[38:39], v[42:43], v[42:43]
	s_nop 0
	v_add_f32_e32 v39, v39, v49
	v_add_f32_e32 v38, v38, v39
	ds_bpermute_b32 v39, v62, v38
	s_waitcnt lgkmcnt(0)
; __device__ __forceinline__ unsigned cvt_pk_bf16(float lo, float hi) { unsigned r; asm volatile("v_cvt_pk_bf16_f32 %0, %1, %2" : "=v"(r) : "v"(lo), "v"(hi)); return r; }
; __device__ __forceinline__ float bflo(unsigned w) { return __uint_as_float(w << 16); }
; __device__ __forceinline__ float bfhi(unsigned w) { return __uint_as_float(w & 0xffff0000u); }
; #define LAS __attribute__((address_space(3)))
; __device__ __forceinline__ void swa_compute(SwaRaw& R, int b, int kvh, int nb, const bf16_t* P, const float* __restrict__ qg, const float* __restrict__ kg, const float* __restrict__ sinks, bf16_t* OB, LAS unsigned char* lds, int tid) {
;     ...
;         for (int p = 0; p < 4; ++p) { const int ki = (tid >> 3) + 64 * p; const u32x4 raw = R.k[p], rv = R.v[p];
;             float x[8] = {bflo(raw.x), bfhi(raw.x), bflo(raw.y), bfhi(raw.y), bflo(raw.z), bfhi(raw.z), bflo(raw.w), bfhi(raw.w)};
;             float ss = 0.f;
; #pragma unroll
;             for (int e = 0; e < 8; ++e) ss += x[e] * x[e];
;             ss += __shfl_xor(ss, 1); ss += __shfl_xor(ss, 2); ss += __shfl_xor(ss, 4);
;             const float rs = 1.0f / sqrtf(ss * (1.0f / 64.0f) + EPS);
;             u32x4 w; w.x = cvt_pk_bf16(x[0] * rs * g0.x, x[1] * rs * g0.y); w.y = cvt_pk_bf16(x[2] * rs * g0.z, x[3] * rs * g0.w); w.z = cvt_pk_bf16(x[4] * rs * g1.x, x[5] * rs * g1.y); w.w = cvt_pk_bf16(x[6] * rs * g1.z, x[7] * rs * g1.w);
;             *(LAS u32x4*)(Ks + ki * 72 + ch * 8) = w;
;             *(LAS u32x4*)(Vr + ki * 72 + ch * 8) = rv; }
	v_add_f32_e32 v38, v38, v39
	ds_bpermute_b32 v39, v63, v38
	s_waitcnt lgkmcnt(0)
	v_add_f32_e32 v38, v38, v39
	ds_bpermute_b32 v39, v64, v38
	s_waitcnt lgkmcnt(0)
	v_add_f32_e32 v38, v38, v39
	v_fmamk_f32 v38, v38, 0x3c800000, v95
	v_cmp_gt_f32_e32 vcc, s91, v38
	v_mul_f32_e32 v39, 0x4f800000, v38
	s_nop 0
	v_cndmask_b32_e32 v38, v38, v39, vcc
	v_sqrt_f32_e32 v39, v38
	s_nop 0
	v_add_u32_e32 v41, -1, v39
	v_fma_f32 v49, -v41, v39, v38
	v_cmp_ge_f32_e64 s[4:5], 0, v49
	v_add_u32_e32 v49, 1, v39
	s_nop 0
	v_cndmask_b32_e64 v41, v39, v41, s[4:5]
	v_fma_f32 v39, -v49, v39, v38
	v_cmp_lt_f32_e64 s[4:5], 0, v39
	s_nop 1
	v_cndmask_b32_e64 v39, v41, v49, s[4:5]
	v_mul_f32_e32 v41, 0x37800000, v39
	v_cndmask_b32_e32 v39, v39, v41, vcc
	v_cmp_class_f32_e32 vcc, v38, v172
	s_nop 1
	v_cndmask_b32_e32 v38, v39, v38, vcc
	v_div_scale_f32 v39, s[4:5], v38, v38, 1.0
	v_rcp_f32_e32 v41, v39
	s_nop 0
	v_fma_f32 v49, -v39, v41, 1.0
	v_fmac_f32_e32 v41, v49, v41
	v_div_scale_f32 v49, vcc, 1.0, v38, 1.0
	v_mul_f32_e32 v50, v49, v41
	v_fma_f32 v51, -v39, v50, v49
	v_fmac_f32_e32 v50, v51, v41
	v_fma_f32 v39, -v39, v50, v49
	v_div_fmas_f32 v39, v39, v41, v50
	v_div_fixup_f32 v41, v39, v38, 1.0
	v_mul_f32_e32 v38, v41, v44
	v_mul_f32_e32 v39, v41, v45
	v_mul_f32_e32 v38, v18, v38
	v_mul_f32_e32 v39, v19, v39
	v_cvt_pk_bf16_f32 v38, v38, v39
	v_mul_f32_e32 v39, v41, v46
	v_mul_f32_e32 v44, v41, v47
	v_mul_f32_e32 v39, v20, v39
	v_mul_f32_e32 v44, v21, v44
	v_cvt_pk_bf16_f32 v39, v39, v44
	v_mul_f32_e32 v44, v41, v48
	v_mul_f32_e32 v40, v41, v40
	v_mul_f32_e32 v43, v41, v43
	v_mul_f32_e32 v41, v41, v42
	v_mul_f32_e32 v40, v15, v40
	v_mul_f32_e32 v41, v17, v41
	v_mul_f32_e32 v44, v14, v44
	v_cvt_pk_bf16_f32 v40, v44, v40
	v_mul_f32_e32 v43, v16, v43
	v_cvt_pk_bf16_f32 v41, v43, v41
	ds_write_b128 v162, v[38:41] offset:27648
	ds_write_b128 v162, v[34:37] offset:64512
	v_and_b32_e32 v37, 0xffff0000, v30
	v_lshlrev_b32_e32 v36, 16, v30
	v_mul_f32_e32 v41, v37, v37
	v_lshlrev_b32_e32 v38, 16, v31
	v_fmac_f32_e32 v41, v36, v36
	v_and_b32_e32 v39, 0xffff0000, v31
	v_fmac_f32_e32 v41, v38, v38
	v_lshlrev_b32_e32 v40, 16, v32
	v_fmac_f32_e32 v41, v39, v39
	v_and_b32_e32 v32, 0xffff0000, v32
	v_fmac_f32_e32 v41, v40, v40
	v_and_b32_e32 v34, 0xffff0000, v33
	v_lshlrev_b32_e32 v35, 16, v33
	v_fmac_f32_e32 v41, v32, v32
	v_pk_mul_f32 v[30:31], v[34:35], v[34:35]
	s_nop 0
	v_add_f32_e32 v31, v31, v41
	v_add_f32_e32 v30, v30, v31
	ds_bpermute_b32 v31, v62, v30
	s_waitcnt lgkmcnt(0)
	v_add_f32_e32 v30, v30, v31
	ds_bpermute_b32 v31, v63, v30
	s_waitcnt lgkmcnt(0)
	v_add_f32_e32 v30, v30, v31
	ds_bpermute_b32 v31, v64, v30
	s_waitcnt lgkmcnt(0)
	v_add_f32_e32 v30, v30, v31
	v_fmamk_f32 v30, v30, 0x3c800000, v95
	v_cmp_gt_f32_e32 vcc, s91, v30
	v_mul_f32_e32 v31, 0x4f800000, v30
	s_nop 0
	v_cndmask_b32_e32 v30, v30, v31, vcc
	v_sqrt_f32_e32 v31, v30
	s_nop 0
	v_add_u32_e32 v33, -1, v31
	v_fma_f32 v41, -v33, v31, v30
	v_cmp_ge_f32_e64 s[4:5], 0, v41
	v_add_u32_e32 v41, 1, v31
	s_nop 0
	v_cndmask_b32_e64 v33, v31, v33, s[4:5]
	v_fma_f32 v31, -v41, v31, v30
	v_cmp_lt_f32_e64 s[4:5], 0, v31
	s_nop 1
	v_cndmask_b32_e64 v31, v33, v41, s[4:5]
	v_mul_f32_e32 v33, 0x37800000, v31
	v_cndmask_b32_e32 v31, v31, v33, vcc
	v_cmp_class_f32_e32 vcc, v30, v172
	s_nop 1
	v_cndmask_b32_e32 v30, v31, v30, vcc
	v_div_scale_f32 v31, s[4:5], v30, v30, 1.0
	v_rcp_f32_e32 v33, v31
	s_nop 0
	v_fma_f32 v41, -v31, v33, 1.0
	v_fmac_f32_e32 v33, v41, v33
	v_div_scale_f32 v41, vcc, 1.0, v30, 1.0
	v_mul_f32_e32 v42, v41, v33
	v_fma_f32 v43, -v31, v42, v41
	v_fmac_f32_e32 v42, v43, v33
	v_fma_f32 v31, -v31, v42, v41
	v_div_fmas_f32 v31, v31, v33, v42
	v_div_fixup_f32 v33, v31, v30, 1.0
	v_mul_f32_e32 v30, v33, v36
	v_mul_f32_e32 v31, v33, v37
	v_mul_f32_e32 v30, v18, v30
	v_mul_f32_e32 v31, v19, v31
	v_cvt_pk_bf16_f32 v30, v30, v31
	v_mul_f32_e32 v31, v33, v38
	v_mul_f32_e32 v36, v33, v39
	v_mul_f32_e32 v31, v20, v31
	v_mul_f32_e32 v36, v21, v36
	v_cvt_pk_bf16_f32 v31, v31, v36
	v_mul_f32_e32 v36, v33, v40
	v_mul_f32_e32 v32, v33, v32
	v_mul_f32_e32 v35, v33, v35
	v_mul_f32_e32 v33, v33, v34
	v_mul_f32_e32 v32, v15, v32
	v_mul_f32_e32 v33, v17, v33
	v_mul_f32_e32 v36, v14, v36
	v_cvt_pk_bf16_f32 v32, v36, v32
	v_mul_f32_e32 v35, v16, v35
	v_cvt_pk_bf16_f32 v33, v35, v33
	ds_write_b128 v162, v[30:33] offset:36864
	ds_write_b128 v163, v[26:29] offset:18432
	v_and_b32_e32 v27, 0xffff0000, v22
	v_lshlrev_b32_e32 v26, 16, v22
	v_mul_f32_e32 v32, v27, v27
	v_lshlrev_b32_e32 v28, 16, v23
	v_fmac_f32_e32 v32, v26, v26
	v_and_b32_e32 v29, 0xffff0000, v23
	v_fmac_f32_e32 v32, v28, v28
	v_lshlrev_b32_e32 v30, 16, v24
	v_fmac_f32_e32 v32, v29, v29
	v_and_b32_e32 v31, 0xffff0000, v24
	v_fmac_f32_e32 v32, v30, v30
	v_and_b32_e32 v22, 0xffff0000, v25
	v_lshlrev_b32_e32 v23, 16, v25
	v_fmac_f32_e32 v32, v31, v31
	v_pk_mul_f32 v[24:25], v[22:23], v[22:23]
	s_nop 0
	v_add_f32_e32 v25, v25, v32
	v_add_f32_e32 v24, v24, v25
	ds_bpermute_b32 v25, v62, v24
	s_waitcnt lgkmcnt(0)
	v_add_f32_e32 v24, v24, v25
	ds_bpermute_b32 v25, v63, v24
	s_waitcnt lgkmcnt(0)
	v_add_f32_e32 v24, v24, v25
	ds_bpermute_b32 v25, v64, v24
	s_waitcnt lgkmcnt(0)
; __device__ __forceinline__ unsigned cvt_pk_bf16(float lo, float hi) { unsigned r; asm volatile("v_cvt_pk_bf16_f32 %0, %1, %2" : "=v"(r) : "v"(lo), "v"(hi)); return r; }
; __device__ __forceinline__ float bflo(unsigned w) { return __uint_as_float(w << 16); }
; __device__ __forceinline__ float bfhi(unsigned w) { return __uint_as_float(w & 0xffff0000u); }
; #define LAS __attribute__((address_space(3)))
; __device__ __forceinline__ void swa_compute(SwaRaw& R, int b, int kvh, int nb, const bf16_t* P, const float* __restrict__ qg, const float* __restrict__ kg, const float* __restrict__ sinks, bf16_t* OB, LAS unsigned char* lds, int tid) {
;     ...
;         for (int p = 0; p < 4; ++p) { const int ki = (tid >> 3) + 64 * p; const u32x4 raw = R.k[p], rv = R.v[p];
;             float x[8] = {bflo(raw.x), bfhi(raw.x), bflo(raw.y), bfhi(raw.y), bflo(raw.z), bfhi(raw.z), bflo(raw.w), bfhi(raw.w)};
;             float ss = 0.f;
; #pragma unroll
;             for (int e = 0; e < 8; ++e) ss += x[e] * x[e];
;             ss += __shfl_xor(ss, 1); ss += __shfl_xor(ss, 2); ss += __shfl_xor(ss, 4);
;             const float rs = 1.0f / sqrtf(ss * (1.0f / 64.0f) + EPS);
;             u32x4 w; w.x = cvt_pk_bf16(x[0] * rs * g0.x, x[1] * rs * g0.y); w.y = cvt_pk_bf16(x[2] * rs * g0.z, x[3] * rs * g0.w); w.z = cvt_pk_bf16(x[4] * rs * g1.x, x[5] * rs * g1.y); w.w = cvt_pk_bf16(x[6] * rs * g1.z, x[7] * rs * g1.w);
;             *(LAS u32x4*)(Ks + ki * 72 + ch * 8) = w;
;             *(LAS u32x4*)(Vr + ki * 72 + ch * 8) = rv; }
;     }
;     const f32x4 qg0 = *(const f32x4*)(qg + ch * 8), qg1 = *(const f32x4*)(qg + ch * 8 + 4);
;     ...
;         const int qi = wid * 16 + fr; const float sink = sinks[hq]; float m = sink;
; #pragma unroll
;         for (int j = 0; j < 10; ++j)
; #pragma unroll
;             for (int r = 0; r < 4; ++r) { const int ki = (kt0 + j) * 16 + 4 * fq + r; const bool valid = (ki > qi) && (ki <= qi + 128) && ((nb > 0) || (ki >= 128));
;                 s[j][r] = valid ? s[j][r] : -INFINITY; m = fmaxf(m, s[j][r]); }
	v_add_f32_e32 v24, v24, v25
	v_fmamk_f32 v24, v24, 0x3c800000, v95
	v_cmp_gt_f32_e32 vcc, s91, v24
	v_mul_f32_e32 v25, 0x4f800000, v24
	s_nop 0
	v_cndmask_b32_e32 v24, v24, v25, vcc
	v_sqrt_f32_e32 v25, v24
	s_nop 0
	v_add_u32_e32 v32, -1, v25
	v_fma_f32 v33, -v32, v25, v24
	v_cmp_ge_f32_e64 s[4:5], 0, v33
	v_add_u32_e32 v33, 1, v25
	s_nop 0
	v_cndmask_b32_e64 v32, v25, v32, s[4:5]
	v_fma_f32 v25, -v33, v25, v24
	v_cmp_lt_f32_e64 s[4:5], 0, v25
	s_nop 1
	v_cndmask_b32_e64 v25, v32, v33, s[4:5]
	v_mul_f32_e32 v32, 0x37800000, v25
	v_cndmask_b32_e32 v25, v25, v32, vcc
	v_cmp_class_f32_e32 vcc, v24, v172
	s_nop 1
	v_cndmask_b32_e32 v24, v25, v24, vcc
	v_div_scale_f32 v25, s[4:5], v24, v24, 1.0
	v_rcp_f32_e32 v32, v25
	s_lshl_b32 s4, s8, 4
	v_fma_f32 v33, -v25, v32, 1.0
	v_fmac_f32_e32 v32, v33, v32
	v_div_scale_f32 v33, vcc, 1.0, v24, 1.0
	v_mul_f32_e32 v34, v33, v32
	v_fma_f32 v35, -v25, v34, v33
	v_fmac_f32_e32 v34, v35, v32
	v_fma_f32 v25, -v25, v34, v33
	v_div_fmas_f32 v25, v25, v32, v34
	v_div_fixup_f32 v24, v25, v24, 1.0
	v_mul_f32_e32 v25, v24, v26
	v_mul_f32_e32 v18, v18, v25
	v_mul_f32_e32 v25, v24, v27
	v_mul_f32_e32 v19, v19, v25
	v_cvt_pk_bf16_f32 v18, v18, v19
	v_mul_f32_e32 v19, v24, v28
	v_mul_f32_e32 v19, v20, v19
	v_mul_f32_e32 v20, v24, v29
	v_mul_f32_e32 v20, v21, v20
	v_cvt_pk_bf16_f32 v19, v19, v20
	v_mul_f32_e32 v20, v24, v30
	v_mul_f32_e32 v14, v14, v20
	v_mul_f32_e32 v20, v24, v31
	v_mul_f32_e32 v15, v15, v20
	v_cvt_pk_bf16_f32 v20, v14, v15
	v_mul_f32_e32 v14, v24, v23
	v_mul_f32_e32 v15, v24, v22
	v_mul_f32_e32 v14, v16, v14
	v_mul_f32_e32 v15, v17, v15
	v_cvt_pk_bf16_f32 v21, v14, v15
	ds_write_b128 v162, v[18:21] offset:46080
	ds_write_b128 v163, v[10:13] offset:27648
	v_or_b32_e32 v18, s4, v91
	s_add_i32 s4, s4, -16
	s_cmp_gt_u32 s6, 63
	s_cselect_b32 s4, s4, 0
	v_add_u32_e32 v19, 0x80, v18
	v_add_u32_e32 v21, s4, v164
	v_or_b32_e32 v32, s4, v161
	v_mul_lo_u32 v66, v21, s59
	v_or_b32_e32 v21, s4, v91
	s_add_i32 s16, s4, 16
	s_add_i32 s24, s4, 32
	s_add_i32 s34, s4, 48
	s_add_i32 s42, s4, 64
	s_add_i32 s50, s4, 0x50
	s_add_i32 s58, s4, 0x60
	s_add_i32 s66, s4, 0x70
	v_sub_co_u32_e32 v31, vcc, s4, v176
	s_add_i32 s78, s4, 0x90
	v_cmp_gt_i32_e64 s[4:5], v32, v18
	v_cmp_le_i32_e64 s[6:7], v32, v19
	s_and_b64 s[6:7], s[4:5], s[6:7]
	v_cmp_lt_i32_e64 s[4:5], s14, v32
	s_or_b64 s[4:5], s[74:75], s[4:5]
	s_and_b64 s[4:5], s[6:7], s[4:5]
	v_cmp_ge_i32_e64 s[6:7], v32, v18
	v_cmp_lt_i32_e64 s[8:9], v32, v19
	s_and_b64 s[8:9], s[6:7], s[8:9]
	v_cmp_lt_i32_e64 s[6:7], s76, v32
	s_or_b64 s[6:7], s[74:75], s[6:7]
	v_or_b32_e32 v33, 2, v32
	s_and_b64 s[6:7], s[8:9], s[6:7]
	v_cmp_gt_i32_e64 s[8:9], v33, v18
	v_cmp_le_i32_e64 s[10:11], v33, v19
	s_and_b64 s[10:11], s[8:9], s[10:11]
	v_cmp_lt_i32_e64 s[8:9], s14, v33
	s_or_b64 s[8:9], s[74:75], s[8:9]
	v_or_b32_e32 v32, 3, v32
	s_and_b64 s[8:9], s[10:11], s[8:9]
	v_cmp_gt_i32_e64 s[10:11], v32, v18
	v_cmp_le_i32_e64 s[12:13], v32, v19
	s_and_b64 s[12:13], s[10:11], s[12:13]
	v_cmp_lt_i32_e64 s[10:11], s14, v32
	s_or_b64 s[10:11], s[74:75], s[10:11]
	v_or_b32_e32 v32, s16, v161
	s_and_b64 s[10:11], s[12:13], s[10:11]
	v_cmp_gt_i32_e64 s[12:13], v32, v18
	v_cmp_le_i32_e64 s[14:15], v32, v19
	s_and_b64 s[12:13], s[12:13], s[14:15]
	s_cmpk_gt_u32 s16, 0x7f
	s_cselect_b64 s[14:15], -1, 0
	v_or_b32_e32 v22, s16, v91
	s_or_b64 s[22:23], s[74:75], s[14:15]
	v_cmp_ge_i32_e64 s[14:15], v32, v18
	v_cmp_lt_i32_e64 s[16:17], v32, v19
	s_and_b64 s[16:17], s[14:15], s[16:17]
	v_cmp_lt_u32_e64 s[14:15], s76, v32
	s_or_b64 s[14:15], s[74:75], s[14:15]
	v_or_b32_e32 v33, 2, v32
	global_load_dwordx4 v[10:13], v[110:111], off
	global_load_dwordx4 v[14:17], v[110:111], off offset:16
	s_and_b64 s[14:15], s[16:17], s[14:15]
	v_cmp_gt_i32_e64 s[16:17], v33, v18
	v_cmp_le_i32_e64 s[18:19], v33, v19
	v_or_b32_e32 v32, 3, v32
	s_and_b64 s[16:17], s[16:17], s[18:19]
	v_cmp_gt_i32_e64 s[18:19], v32, v18
	v_cmp_le_i32_e64 s[20:21], v32, v19
	s_and_b64 s[18:19], s[18:19], s[20:21]
	v_or_b32_e32 v32, s24, v161
	s_and_b64 s[12:13], s[22:23], s[12:13]
	s_and_b64 s[16:17], s[22:23], s[16:17]
	s_and_b64 s[18:19], s[22:23], s[18:19]
	v_cmp_gt_i32_e64 s[20:21], v32, v18
	v_cmp_le_i32_e64 s[22:23], v32, v19
	s_and_b64 s[20:21], s[20:21], s[22:23]
	s_cmpk_gt_u32 s24, 0x7f
	s_cselect_b64 s[22:23], -1, 0
	v_or_b32_e32 v23, s24, v91
	s_or_b64 s[30:31], s[74:75], s[22:23]
	v_cmp_ge_i32_e64 s[22:23], v32, v18
	v_cmp_lt_i32_e64 s[24:25], v32, v19
	s_and_b64 s[24:25], s[22:23], s[24:25]
	v_cmp_lt_u32_e64 s[22:23], s76, v32
	s_or_b64 s[22:23], s[74:75], s[22:23]
	v_or_b32_e32 v33, 2, v32
	s_and_b64 s[22:23], s[24:25], s[22:23]
	v_cmp_gt_i32_e64 s[24:25], v33, v18
	v_cmp_le_i32_e64 s[26:27], v33, v19
	v_or_b32_e32 v32, 3, v32
	s_and_b64 s[24:25], s[24:25], s[26:27]
	v_cmp_gt_i32_e64 s[26:27], v32, v18
	v_cmp_le_i32_e64 s[28:29], v32, v19
	s_and_b64 s[26:27], s[26:27], s[28:29]
	v_or_b32_e32 v32, s34, v161
	s_and_b64 s[20:21], s[30:31], s[20:21]
	s_and_b64 s[24:25], s[30:31], s[24:25]
	s_and_b64 s[26:27], s[30:31], s[26:27]
	v_cmp_gt_i32_e64 s[28:29], v32, v18
	v_cmp_le_i32_e64 s[30:31], v32, v19
	s_and_b64 s[28:29], s[28:29], s[30:31]
	s_cmpk_gt_u32 s34, 0x7f
	s_cselect_b64 s[30:31], -1, 0
	v_or_b32_e32 v24, s34, v91
	s_or_b64 s[40:41], s[74:75], s[30:31]
	v_cmp_ge_i32_e64 s[30:31], v32, v18
	v_cmp_lt_i32_e64 s[34:35], v32, v19
	s_and_b64 s[34:35], s[30:31], s[34:35]
	v_cmp_lt_u32_e64 s[30:31], s76, v32
	s_or_b64 s[30:31], s[74:75], s[30:31]
	v_or_b32_e32 v33, 2, v32
	s_and_b64 s[30:31], s[34:35], s[30:31]
	v_cmp_gt_i32_e64 s[34:35], v33, v18
	v_cmp_le_i32_e64 s[36:37], v33, v19
	v_or_b32_e32 v32, 3, v32
; __device__ __forceinline__ unsigned cvt_pk_bf16(float lo, float hi) { unsigned r; asm volatile("v_cvt_pk_bf16_f32 %0, %1, %2" : "=v"(r) : "v"(lo), "v"(hi)); return r; }
; #define LAS __attribute__((address_space(3)))
; #define MFMA16(a, b, c) __builtin_amdgcn_mfma_f32_16x16x32_bf16((a), (b), (c), 0, 0, 0)
; __device__ __forceinline__ void swa_compute(SwaRaw& R, int b, int kvh, int nb, const bf16_t* P, const float* __restrict__ qg, const float* __restrict__ kg, const float* __restrict__ sinks, bf16_t* OB, LAS unsigned char* lds, int tid) {
;     ...
;         const int qi = wid * 16 + fr; const float sink = sinks[hq]; float m = sink;
; #pragma unroll
;         for (int j = 0; j < 10; ++j)
; #pragma unroll
;             for (int r = 0; r < 4; ++r) { const int ki = (kt0 + j) * 16 + 4 * fq + r; const bool valid = (ki > qi) && (ki <= qi + 128) && ((nb > 0) || (ki >= 128));
;                 s[j][r] = valid ? s[j][r] : -INFINITY; m = fmaxf(m, s[j][r]); }
;     ...
;             for (int ks = 0; ks < 5; ++ks) { const LAS bf16_t* vp = Vr + (kt0 * 16 + ks * 32 + 8 * fq + (fr >> 2)) * 72 + dt * 16 + 4 * (fr & 3);
;                 const v4i16_t lo = __builtin_amdgcn_ds_read_tr16_b64_v4i16((LAS v4i16_t*)vp), hi = __builtin_amdgcn_ds_read_tr16_b64_v4i16((LAS v4i16_t*)(vp + 4 * 72));
;                 const bf16x8 vf = {lo[0], lo[1], lo[2], lo[3], hi[0], hi[1], hi[2], hi[3]};
;                 acc = MFMA16(vf, ldfrag(Pw, 168, fr, ks * 32 + 8 * fq), acc); }
;             u32x2 w; w.x = cvt_pk_bf16(acc[0] * inv, acc[1] * inv); w.y = cvt_pk_bf16(acc[2] * inv, acc[3] * inv);
;             *(u32x2*)(OB + (rq0 + qi) * 1024 + hq * 64 + dt * 16 + 4 * fq) = w; }
	s_and_b64 s[34:35], s[34:35], s[36:37]
	v_cmp_gt_i32_e64 s[36:37], v32, v18
	v_cmp_le_i32_e64 s[38:39], v32, v19
	s_and_b64 s[36:37], s[36:37], s[38:39]
	v_or_b32_e32 v32, s42, v161
	s_and_b64 s[28:29], s[40:41], s[28:29]
	s_and_b64 s[34:35], s[40:41], s[34:35]
	s_and_b64 s[36:37], s[40:41], s[36:37]
	v_cmp_gt_i32_e64 s[38:39], v32, v18
	v_cmp_le_i32_e64 s[40:41], v32, v19
	s_and_b64 s[38:39], s[38:39], s[40:41]
	s_cmpk_gt_u32 s42, 0x7f
	s_cselect_b64 s[40:41], -1, 0
	v_or_b32_e32 v25, s42, v91
	s_or_b64 s[48:49], s[74:75], s[40:41]
	v_cmp_ge_i32_e64 s[40:41], v32, v18
	v_cmp_lt_i32_e64 s[42:43], v32, v19
	s_and_b64 s[42:43], s[40:41], s[42:43]
	v_cmp_lt_u32_e64 s[40:41], s76, v32
	s_or_b64 s[40:41], s[74:75], s[40:41]
	v_or_b32_e32 v33, 2, v32
	s_and_b64 s[40:41], s[42:43], s[40:41]
	v_cmp_gt_i32_e64 s[42:43], v33, v18
	v_cmp_le_i32_e64 s[44:45], v33, v19
	v_or_b32_e32 v32, 3, v32
	s_and_b64 s[42:43], s[42:43], s[44:45]
	v_cmp_gt_i32_e64 s[44:45], v32, v18
	v_cmp_le_i32_e64 s[46:47], v32, v19
	s_and_b64 s[44:45], s[44:45], s[46:47]
	v_or_b32_e32 v32, s50, v161
	s_and_b64 s[38:39], s[48:49], s[38:39]
	s_and_b64 s[42:43], s[48:49], s[42:43]
	s_and_b64 s[44:45], s[48:49], s[44:45]
	v_cmp_gt_i32_e64 s[46:47], v32, v18
	v_cmp_le_i32_e64 s[48:49], v32, v19
	s_and_b64 s[46:47], s[46:47], s[48:49]
	s_cmpk_gt_u32 s50, 0x7f
	s_cselect_b64 s[48:49], -1, 0
	v_or_b32_e32 v26, s50, v91
	s_or_b64 s[56:57], s[74:75], s[48:49]
	v_cmp_ge_i32_e64 s[48:49], v32, v18
	v_cmp_lt_i32_e64 s[50:51], v32, v19
	s_and_b64 s[50:51], s[48:49], s[50:51]
	v_cmp_lt_u32_e64 s[48:49], s76, v32
	s_or_b64 s[48:49], s[74:75], s[48:49]
	v_or_b32_e32 v33, 2, v32
	s_and_b64 s[48:49], s[50:51], s[48:49]
	v_cmp_gt_i32_e64 s[50:51], v33, v18
	v_cmp_le_i32_e64 s[52:53], v33, v19
	v_or_b32_e32 v32, 3, v32
	s_and_b64 s[50:51], s[50:51], s[52:53]
	v_cmp_gt_i32_e64 s[52:53], v32, v18
	v_cmp_le_i32_e64 s[54:55], v32, v19
	s_and_b64 s[52:53], s[52:53], s[54:55]
	v_or_b32_e32 v32, s58, v161
	s_and_b64 s[46:47], s[56:57], s[46:47]
	s_and_b64 s[50:51], s[56:57], s[50:51]
	s_and_b64 s[52:53], s[56:57], s[52:53]
	v_cmp_gt_i32_e64 s[54:55], v32, v18
	v_cmp_le_i32_e64 s[56:57], v32, v19
	s_and_b64 s[54:55], s[54:55], s[56:57]
	s_cmpk_gt_u32 s58, 0x7f
	v_or_b32_e32 v27, s58, v91
	v_or_b32_e32 v28, s66, v91
	v_or_b32_e32 v29, v31, v91
	v_or_b32_e32 v30, s78, v91
	s_cselect_b64 s[56:57], -1, 0
	v_mul_lo_u32 v20, v18, s59
	v_mul_lo_u32 v21, v21, s59
	v_mul_lo_u32 v22, v22, s59
	v_mul_lo_u32 v23, v23, s59
	v_mul_lo_u32 v24, v24, s59
	v_mul_lo_u32 v25, v25, s59
	v_mul_lo_u32 v26, v26, s59
	v_mul_lo_u32 v27, v27, s59
	v_mul_lo_u32 v28, v28, s59
	v_mul_lo_u32 v29, v29, s59
	v_mul_lo_u32 v30, v30, s59
	s_or_b64 s[64:65], s[74:75], s[56:57]
	v_cmp_ge_i32_e64 s[56:57], v32, v18
	v_cmp_lt_i32_e64 s[58:59], v32, v19
	s_and_b64 s[58:59], s[56:57], s[58:59]
	v_cmp_lt_u32_e64 s[56:57], s76, v32
	s_or_b64 s[56:57], s[74:75], s[56:57]
	v_or_b32_e32 v33, 2, v32
	s_and_b64 s[56:57], s[58:59], s[56:57]
	v_cmp_gt_i32_e64 s[58:59], v33, v18
	v_cmp_le_i32_e64 s[60:61], v33, v19
	v_or_b32_e32 v32, 3, v32
	s_and_b64 s[58:59], s[58:59], s[60:61]
	v_cmp_gt_i32_e64 s[60:61], v32, v18
	v_cmp_le_i32_e64 s[62:63], v32, v19
	s_and_b64 s[60:61], s[60:61], s[62:63]
	v_or_b32_e32 v32, s66, v161
	s_and_b64 s[54:55], s[64:65], s[54:55]
	s_and_b64 s[58:59], s[64:65], s[58:59]
	s_and_b64 s[60:61], s[64:65], s[60:61]
	v_cmp_gt_i32_e64 s[62:63], v32, v18
	v_cmp_le_i32_e64 s[64:65], v32, v19
	s_and_b64 s[62:63], s[62:63], s[64:65]
	s_cmpk_gt_u32 s66, 0x7f
	s_cselect_b64 s[64:65], -1, 0
	s_or_b64 s[72:73], s[74:75], s[64:65]
	v_cmp_ge_i32_e64 s[64:65], v32, v18
	v_cmp_lt_i32_e64 s[66:67], v32, v19
	s_and_b64 s[66:67], s[64:65], s[66:67]
	v_cmp_lt_u32_e64 s[64:65], s76, v32
	s_or_b64 s[64:65], s[74:75], s[64:65]
	v_or_b32_e32 v33, 2, v32
	s_and_b64 s[64:65], s[66:67], s[64:65]
	v_cmp_gt_i32_e64 s[66:67], v33, v18
	v_cmp_le_i32_e64 s[68:69], v33, v19
	v_or_b32_e32 v32, 3, v32
	s_and_b64 s[66:67], s[66:67], s[68:69]
	v_cmp_gt_i32_e64 s[68:69], v32, v18
	v_cmp_le_i32_e64 s[70:71], v32, v19
	s_and_b64 s[68:69], s[68:69], s[70:71]
	v_or_b32_e32 v31, v31, v161
	s_and_b64 s[62:63], s[72:73], s[62:63]
	s_and_b64 s[66:67], s[72:73], s[66:67]
	s_and_b64 s[68:69], s[72:73], s[68:69]
	v_cmp_gt_i32_e64 s[70:71], v31, v18
	v_cmp_le_i32_e64 s[72:73], v31, v19
	s_and_b64 s[70:71], s[70:71], s[72:73]
	s_or_b64 s[80:81], s[74:75], vcc
	v_cmp_ge_i32_e32 vcc, v31, v18
	v_cmp_lt_i32_e64 s[72:73], v31, v19
	s_and_b64 s[72:73], vcc, s[72:73]
	v_cmp_lt_u32_e32 vcc, s76, v31
	s_or_b64 s[74:75], s[74:75], vcc
	v_or_b32_e32 v32, 2, v31
	s_and_b64 s[72:73], s[72:73], s[74:75]
	v_cmp_gt_i32_e32 vcc, v32, v18
	v_cmp_le_i32_e64 s[74:75], v32, v19
	v_or_b32_e32 v31, 3, v31
	s_and_b64 s[74:75], vcc, s[74:75]
	v_cmp_gt_i32_e32 vcc, v31, v18
	v_cmp_le_i32_e64 s[76:77], v31, v19
	v_or_b32_e32 v31, s78, v161
	s_and_b64 s[76:77], vcc, s[76:77]
	v_cmp_gt_i32_e32 vcc, v31, v18
	v_cmp_le_i32_e64 s[78:79], v31, v19
	s_and_b64 s[70:71], s[80:81], s[70:71]
	s_and_b64 s[74:75], s[80:81], s[74:75]
	s_and_b64 s[76:77], s[80:81], s[76:77]
	s_and_b64 s[78:79], vcc, s[78:79]
	v_cmp_ge_i32_e32 vcc, v31, v18
	v_cmp_lt_i32_e64 s[80:81], v31, v19
	v_or_b32_e32 v32, 2, v31
	s_and_b64 s[80:81], vcc, s[80:81]
	v_cmp_gt_i32_e32 vcc, v32, v18
	v_cmp_le_i32_e64 s[82:83], v32, v19
	v_or_b32_e32 v31, 3, v31
	s_and_b64 s[82:83], vcc, s[82:83]
	v_cmp_gt_i32_e32 vcc, v31, v18
	v_cmp_le_i32_e64 s[84:85], v31, v19
	s_and_b64 s[84:85], vcc, s[84:85]
	s_add_u32 s86, s86, s89
	s_addc_u32 s87, s87, 0
	v_mov_b32_e32 v19, v1
	v_lshl_add_u64 v[34:35], s[86:87], 0, v[88:89]
	v_lshl_add_u64 v[18:19], s[86:87], 0, v[18:19]
	v_mad_u64_u32 v[36:37], vcc, v34, s96, v[0:1]
	v_lshlrev_b64 v[18:19], 11, v[18:19]
	v_add_u32_e32 v31, 0x3600, v66
	v_add_u32_e32 v32, 0x4800, v66
	v_mad_i32_i24 v37, v35, s96, v37
	v_or_b32_e32 v18, s88, v18
	v_lshl_add_u64 v[58:59], v[116:117], 0, v[36:37]
	v_lshl_add_u64 v[60:61], v[118:119], 0, v[18:19]
	s_mov_b64 s[86:87], 0
	v_add_u32_e32 v0, v184, v21
	v_add_u32_e32 v67, v184, v20
	v_add_u32_e32 v68, v184, v22
	v_add_u32_e32 v69, v184, v23
	v_add_u32_e32 v70, v184, v24
	v_add_u32_e32 v71, v184, v25
	v_add_u32_e32 v72, v184, v26
	v_add_u32_e32 v73, v184, v27
	v_add_u32_e32 v76, v184, v28
	v_add_u32_e32 v77, v184, v29
	v_add_u32_e32 v78, v184, v30
	v_add_u32_e32 v79, v165, v31
	v_add_u32_e32 v80, v165, v32
	s_waitcnt vmcnt(0)
	s_branch .LBB0_499
; #define MFMA16(a, b, c) __builtin_amdgcn_mfma_f32_16x16x32_bf16((a), (b), (c), 0, 0, 0)
; #define LBAR() do { asm volatile("s_waitcnt lgkmcnt(0)" ::: "memory"); __builtin_amdgcn_s_barrier(); asm volatile("" ::: "memory"); } while (0)
; __device__ __forceinline__ void swa_compute(SwaRaw& R, int b, int kvh, int nb, const bf16_t* P, const float* __restrict__ qg, const float* __restrict__ kg, const float* __restrict__ sinks, bf16_t* OB, LAS unsigned char* lds, int tid) {
;     ...
;         LBAR();
;         f32x4 s[10];
; #pragma unroll
;         for (int j = 0; j < 10; ++j) { f32x4 acc = {0.f, 0.f, 0.f, 0.f};
; #pragma unroll
;             for (int ks = 0; ks < 2; ++ks) acc = MFMA16(ldfrag(Ks, 72, (kt0 + j) * 16 + fr, ks * 32 + 8 * fq), ldfrag(Qs, 72, wid * 16 + fr, ks * 32 + 8 * fq), acc);
;             s[j] = acc; }
;         const int qi = wid * 16 + fr; const float sink = sinks[hq]; float m = sink;
; #pragma unroll
;         for (int j = 0; j < 10; ++j)
; #pragma unroll
;             for (int r = 0; r < 4; ++r) { const int ki = (kt0 + j) * 16 + 4 * fq + r; const bool valid = (ki > qi) && (ki <= qi + 128) && ((nb > 0) || (ki >= 128));
;                 s[j][r] = valid ? s[j][r] : -INFINITY; m = fmaxf(m, s[j][r]); }
;         m = fmaxf(m, __shfl_xor(m, 16)); m = fmaxf(m, __shfl_xor(m, 32));
.LBB0_498:
	s_waitcnt lgkmcnt(0)
	s_barrier
	s_load_dword s99, s[2:3], 0x0
	ds_read_b128 v[18:21], v0 offset:18432
	ds_read_b128 v[82:85], v67
	ds_read_b128 v[22:25], v0 offset:18496
	ds_read_b128 v[122:125], v67 offset:64
	s_waitcnt lgkmcnt(2)
	v_mfma_f32_16x16x32_bf16 v[18:21], v[18:21], v[82:85], 0
	s_waitcnt lgkmcnt(0)
	v_mfma_f32_16x16x32_bf16 v[54:57], v[22:25], v[122:125], v[18:21]
	ds_read_b128 v[22:25], v68 offset:18496
	s_nop 4
	ds_read_b128 v[18:21], v68 offset:18432
	s_waitcnt lgkmcnt(0)
	v_mfma_f32_16x16x32_bf16 v[18:21], v[18:21], v[82:85], 0
	v_cndmask_b32_e64 v54, v177, v54, s[4:5]
	v_cndmask_b32_e64 v55, v177, v55, s[6:7]
	v_cndmask_b32_e64 v56, v177, v56, s[8:9]
	v_mfma_f32_16x16x32_bf16 v[50:53], v[22:25], v[122:125], v[18:21]
	ds_read_b128 v[22:25], v69 offset:18496
	v_cndmask_b32_e64 v57, v177, v57, s[10:11]
	s_nop 1
	ds_read_b128 v[18:21], v69 offset:18432
	s_waitcnt lgkmcnt(0)
	v_mfma_f32_16x16x32_bf16 v[18:21], v[18:21], v[82:85], 0
	s_nop 0
	v_cndmask_b32_e64 v50, v177, v50, s[12:13]
	v_cndmask_b32_e64 v51, v177, v51, s[14:15]
	v_cndmask_b32_e64 v52, v177, v52, s[16:17]
	v_mfma_f32_16x16x32_bf16 v[46:49], v[22:25], v[122:125], v[18:21]
	ds_read_b128 v[22:25], v70 offset:18496
	v_cndmask_b32_e64 v53, v177, v53, s[18:19]
	s_nop 0
	ds_read_b128 v[18:21], v70 offset:18432
	s_waitcnt lgkmcnt(0)
	v_mfma_f32_16x16x32_bf16 v[18:21], v[18:21], v[82:85], 0
	s_nop 1
	v_cndmask_b32_e64 v46, v177, v46, s[20:21]
	v_cndmask_b32_e64 v47, v177, v47, s[22:23]
	v_cndmask_b32_e64 v48, v177, v48, s[24:25]
	v_mfma_f32_16x16x32_bf16 v[42:45], v[22:25], v[122:125], v[18:21]
	ds_read_b128 v[22:25], v71 offset:18496
	v_cndmask_b32_e64 v49, v177, v49, s[26:27]
	s_nop 0
	ds_read_b128 v[18:21], v71 offset:18432
	s_waitcnt lgkmcnt(0)
	v_mfma_f32_16x16x32_bf16 v[18:21], v[18:21], v[82:85], 0
	s_nop 1
	v_cndmask_b32_e64 v42, v177, v42, s[28:29]
	v_cndmask_b32_e64 v43, v177, v43, s[30:31]
	v_cndmask_b32_e64 v44, v177, v44, s[34:35]
	v_mfma_f32_16x16x32_bf16 v[38:41], v[22:25], v[122:125], v[18:21]
	ds_read_b128 v[22:25], v72 offset:18496
	v_cndmask_b32_e64 v45, v177, v45, s[36:37]
	s_nop 0
	ds_read_b128 v[18:21], v72 offset:18432
	s_waitcnt lgkmcnt(0)
	v_mfma_f32_16x16x32_bf16 v[18:21], v[18:21], v[82:85], 0
	s_nop 1
	v_cndmask_b32_e64 v38, v177, v38, s[38:39]
	v_cndmask_b32_e64 v39, v177, v39, s[40:41]
	v_cndmask_b32_e64 v40, v177, v40, s[42:43]
	v_mfma_f32_16x16x32_bf16 v[34:37], v[22:25], v[122:125], v[18:21]
	ds_read_b128 v[22:25], v73 offset:18496
	v_cndmask_b32_e64 v41, v177, v41, s[44:45]
	s_nop 0
	ds_read_b128 v[18:21], v73 offset:18432
	s_waitcnt lgkmcnt(0)
	v_mfma_f32_16x16x32_bf16 v[18:21], v[18:21], v[82:85], 0
	s_nop 1
	v_cndmask_b32_e64 v34, v177, v34, s[46:47]
	v_cndmask_b32_e64 v35, v177, v35, s[48:49]
	v_cndmask_b32_e64 v36, v177, v36, s[50:51]
	v_mfma_f32_16x16x32_bf16 v[30:33], v[22:25], v[122:125], v[18:21]
	ds_read_b128 v[22:25], v76 offset:18496
	v_cndmask_b32_e64 v37, v177, v37, s[52:53]
	s_nop 0
	ds_read_b128 v[18:21], v76 offset:18432
	s_waitcnt lgkmcnt(0)
	v_mfma_f32_16x16x32_bf16 v[18:21], v[18:21], v[82:85], 0
	s_nop 1
	v_cndmask_b32_e64 v30, v177, v30, s[54:55]
	v_cndmask_b32_e64 v31, v177, v31, s[56:57]
	v_cndmask_b32_e64 v32, v177, v32, s[58:59]
	v_mfma_f32_16x16x32_bf16 v[26:29], v[22:25], v[122:125], v[18:21]
	ds_read_b128 v[22:25], v77 offset:18496
	v_cndmask_b32_e64 v33, v177, v33, s[60:61]
	s_nop 0
	ds_read_b128 v[18:21], v77 offset:18432
	s_waitcnt lgkmcnt(0)
	v_mfma_f32_16x16x32_bf16 v[18:21], v[18:21], v[82:85], 0
	s_nop 1
	v_cndmask_b32_e64 v26, v177, v26, s[62:63]
	v_cndmask_b32_e64 v27, v177, v27, s[64:65]
	v_cndmask_b32_e64 v28, v177, v28, s[66:67]
	v_mfma_f32_16x16x32_bf16 v[22:25], v[22:25], v[122:125], v[18:21]
	v_cndmask_b32_e64 v29, v177, v29, s[68:69]
	s_nop 1
	ds_read_b128 v[18:21], v78 offset:18432
	s_waitcnt lgkmcnt(0)
	v_mfma_f32_16x16x32_bf16 v[18:21], v[18:21], v[82:85], 0
	ds_read_b128 v[82:85], v78 offset:18496
	s_nop 0
	v_cndmask_b32_e64 v22, v177, v22, s[70:71]
	v_cndmask_b32_e64 v23, v177, v23, s[72:73]
	s_waitcnt lgkmcnt(0)
	v_mfma_f32_16x16x32_bf16 v[18:21], v[82:85], v[122:125], v[18:21]
	s_waitcnt lgkmcnt(0)
	v_mov_b32_e32 v81, s99
	v_max3_f32 v82, v81, v54, v55
	v_max3_f32 v82, v82, v56, v57
	v_max3_f32 v82, v82, v50, v51
	v_max3_f32 v82, v82, v52, v53
	v_max3_f32 v82, v82, v46, v47
	v_max3_f32 v82, v82, v48, v49
	v_max3_f32 v82, v82, v42, v43
	v_max3_f32 v82, v82, v44, v45
	v_max3_f32 v82, v82, v38, v39
	v_max3_f32 v82, v82, v40, v41
	v_max3_f32 v82, v82, v34, v35
	v_max3_f32 v82, v82, v36, v37
	v_max3_f32 v82, v82, v30, v31
	v_max3_f32 v82, v82, v32, v33
	v_max3_f32 v82, v82, v26, v27
	v_max3_f32 v82, v82, v28, v29
	v_max3_f32 v82, v82, v22, v23
	v_cndmask_b32_e64 v24, v177, v24, s[74:75]
	v_cndmask_b32_e64 v25, v177, v25, s[76:77]
	v_max3_f32 v82, v82, v24, v25
	v_cndmask_b32_e64 v83, v177, v18, s[78:79]
	v_cndmask_b32_e64 v19, v177, v19, s[80:81]
	v_max3_f32 v18, v82, v83, v19
	v_cndmask_b32_e64 v82, v177, v20, s[82:83]
	v_cndmask_b32_e64 v84, v177, v21, s[84:85]
	v_max3_f32 v18, v18, v82, v84
	ds_bpermute_b32 v20, v74, v18
	s_waitcnt lgkmcnt(0)
	v_max_f32_e32 v20, v20, v20
	v_max_f32_e32 v18, v18, v20
	ds_bpermute_b32 v20, v75, v18
	s_waitcnt lgkmcnt(0)
; __device__ __forceinline__ unsigned cvt_pk_bf16(float lo, float hi) { unsigned r; asm volatile("v_cvt_pk_bf16_f32 %0, %1, %2" : "=v"(r) : "v"(lo), "v"(hi)); return r; }
; #define LAS __attribute__((address_space(3)))
; __device__ __forceinline__ void swa_compute(SwaRaw& R, int b, int kvh, int nb, const bf16_t* P, const float* __restrict__ qg, const float* __restrict__ kg, const float* __restrict__ sinks, bf16_t* OB, LAS unsigned char* lds, int tid) {
;     ...
;         float sum = 0.f;
; #pragma unroll
;         for (int j = 0; j < 10; ++j) {
; #pragma unroll
;             for (int r = 0; r < 4; ++r) { s[j][r] = __expf(s[j][r] - m); sum += s[j][r]; }
;             u32x2 w; w.x = cvt_pk_bf16(s[j][0], s[j][1]); w.y = cvt_pk_bf16(s[j][2], s[j][3]);
;             *(LAS u32x2*)(Pw + fr * 168 + j * 16 + 4 * fq) = w; }
;         sum += __shfl_xor(sum, 16); sum += __shfl_xor(sum, 32);
	v_max_f32_e32 v20, v20, v20
	v_max_f32_e32 v18, v18, v20
	v_sub_f32_e32 v20, v54, v18
	v_mul_f32_e32 v20, 0x3fb8aa3b, v20
	v_sub_f32_e32 v54, v55, v18
	v_exp_f32_e32 v20, v20
	v_mul_f32_e32 v54, 0x3fb8aa3b, v54
	v_sub_f32_e32 v55, v56, v18
	v_exp_f32_e32 v54, v54
	v_mul_f32_e32 v55, 0x3fb8aa3b, v55
	v_sub_f32_e32 v56, v57, v18
	v_exp_f32_e32 v55, v55
	v_mul_f32_e32 v56, 0x3fb8aa3b, v56
	v_exp_f32_e32 v56, v56
	v_add_f32_e32 v21, 0, v20
	v_add_f32_e32 v21, v54, v21
	v_add_f32_e32 v21, v55, v21
	v_cvt_pk_bf16_f32 v20, v20, v54
	v_add_f32_e32 v57, v56, v21
	v_cvt_pk_bf16_f32 v21, v55, v56
	ds_write_b64 v65, v[20:21]
	v_sub_f32_e32 v20, v50, v18
	v_mul_f32_e32 v20, 0x3fb8aa3b, v20
	v_sub_f32_e32 v50, v51, v18
	v_exp_f32_e32 v20, v20
	v_mul_f32_e32 v50, 0x3fb8aa3b, v50
	v_sub_f32_e32 v51, v52, v18
	v_exp_f32_e32 v50, v50
	v_mul_f32_e32 v51, 0x3fb8aa3b, v51
	v_sub_f32_e32 v52, v53, v18
	v_exp_f32_e32 v51, v51
	v_mul_f32_e32 v52, 0x3fb8aa3b, v52
	v_exp_f32_e32 v52, v52
	v_add_f32_e32 v21, v20, v57
	v_add_f32_e32 v21, v50, v21
	v_add_f32_e32 v21, v51, v21
	v_cvt_pk_bf16_f32 v20, v20, v50
	v_add_f32_e32 v53, v52, v21
	v_cvt_pk_bf16_f32 v21, v51, v52
	ds_write_b64 v65, v[20:21] offset:32
	v_sub_f32_e32 v20, v46, v18
	v_mul_f32_e32 v20, 0x3fb8aa3b, v20
	v_sub_f32_e32 v46, v47, v18
	v_exp_f32_e32 v20, v20
	v_mul_f32_e32 v46, 0x3fb8aa3b, v46
	v_sub_f32_e32 v47, v48, v18
	v_exp_f32_e32 v46, v46
	v_mul_f32_e32 v47, 0x3fb8aa3b, v47
	v_sub_f32_e32 v48, v49, v18
	v_exp_f32_e32 v47, v47
	v_mul_f32_e32 v48, 0x3fb8aa3b, v48
	v_exp_f32_e32 v48, v48
	v_add_f32_e32 v21, v20, v53
	v_add_f32_e32 v21, v46, v21
	v_add_f32_e32 v21, v47, v21
	v_cvt_pk_bf16_f32 v20, v20, v46
	v_add_f32_e32 v49, v48, v21
	v_cvt_pk_bf16_f32 v21, v47, v48
	ds_write_b64 v65, v[20:21] offset:64
	v_sub_f32_e32 v20, v42, v18
	v_mul_f32_e32 v20, 0x3fb8aa3b, v20
	v_sub_f32_e32 v42, v43, v18
	v_exp_f32_e32 v20, v20
	v_mul_f32_e32 v42, 0x3fb8aa3b, v42
	v_sub_f32_e32 v43, v44, v18
	v_exp_f32_e32 v42, v42
	v_mul_f32_e32 v43, 0x3fb8aa3b, v43
	v_sub_f32_e32 v44, v45, v18
	v_exp_f32_e32 v43, v43
	v_mul_f32_e32 v44, 0x3fb8aa3b, v44
	v_exp_f32_e32 v44, v44
	v_add_f32_e32 v21, v20, v49
	v_add_f32_e32 v21, v42, v21
	v_add_f32_e32 v21, v43, v21
	v_cvt_pk_bf16_f32 v20, v20, v42
	v_add_f32_e32 v45, v44, v21
	v_cvt_pk_bf16_f32 v21, v43, v44
	ds_write_b64 v65, v[20:21] offset:96
	v_sub_f32_e32 v20, v38, v18
	v_mul_f32_e32 v20, 0x3fb8aa3b, v20
	v_sub_f32_e32 v38, v39, v18
	v_exp_f32_e32 v20, v20
	v_mul_f32_e32 v38, 0x3fb8aa3b, v38
	v_sub_f32_e32 v39, v40, v18
	v_exp_f32_e32 v38, v38
	v_mul_f32_e32 v39, 0x3fb8aa3b, v39
	v_sub_f32_e32 v40, v41, v18
	v_exp_f32_e32 v39, v39
	v_mul_f32_e32 v40, 0x3fb8aa3b, v40
	v_exp_f32_e32 v40, v40
	v_add_f32_e32 v21, v20, v45
	v_add_f32_e32 v21, v38, v21
	v_add_f32_e32 v21, v39, v21
	v_cvt_pk_bf16_f32 v20, v20, v38
	v_add_f32_e32 v41, v40, v21
	v_cvt_pk_bf16_f32 v21, v39, v40
	ds_write_b64 v65, v[20:21] offset:128
	v_sub_f32_e32 v20, v34, v18
	v_mul_f32_e32 v20, 0x3fb8aa3b, v20
	v_sub_f32_e32 v34, v35, v18
	v_exp_f32_e32 v20, v20
	v_mul_f32_e32 v34, 0x3fb8aa3b, v34
	v_sub_f32_e32 v35, v36, v18
	v_exp_f32_e32 v34, v34
	v_mul_f32_e32 v35, 0x3fb8aa3b, v35
	v_sub_f32_e32 v36, v37, v18
	v_exp_f32_e32 v35, v35
	v_mul_f32_e32 v36, 0x3fb8aa3b, v36
	v_exp_f32_e32 v36, v36
	v_add_f32_e32 v21, v20, v41
	v_add_f32_e32 v21, v34, v21
	v_add_f32_e32 v21, v35, v21
	v_cvt_pk_bf16_f32 v20, v20, v34
	v_add_f32_e32 v37, v36, v21
	v_cvt_pk_bf16_f32 v21, v35, v36
	ds_write_b64 v65, v[20:21] offset:160
	v_sub_f32_e32 v20, v30, v18
	v_mul_f32_e32 v20, 0x3fb8aa3b, v20
	v_sub_f32_e32 v30, v31, v18
	v_exp_f32_e32 v20, v20
	v_mul_f32_e32 v30, 0x3fb8aa3b, v30
	v_sub_f32_e32 v31, v32, v18
	v_exp_f32_e32 v30, v30
	v_mul_f32_e32 v31, 0x3fb8aa3b, v31
	v_sub_f32_e32 v32, v33, v18
	v_exp_f32_e32 v31, v31
	v_mul_f32_e32 v32, 0x3fb8aa3b, v32
	v_exp_f32_e32 v32, v32
	v_add_f32_e32 v21, v20, v37
	v_add_f32_e32 v21, v30, v21
	v_add_f32_e32 v21, v31, v21
	v_cvt_pk_bf16_f32 v20, v20, v30
	v_add_f32_e32 v33, v32, v21
	v_cvt_pk_bf16_f32 v21, v31, v32
	ds_write_b64 v65, v[20:21] offset:192
	v_sub_f32_e32 v20, v26, v18
	v_mul_f32_e32 v20, 0x3fb8aa3b, v20
	v_sub_f32_e32 v26, v27, v18
	v_exp_f32_e32 v20, v20
	v_mul_f32_e32 v26, 0x3fb8aa3b, v26
	v_sub_f32_e32 v27, v28, v18
	v_exp_f32_e32 v26, v26
	v_mul_f32_e32 v27, 0x3fb8aa3b, v27
	v_sub_f32_e32 v28, v29, v18
	v_exp_f32_e32 v27, v27
	v_mul_f32_e32 v28, 0x3fb8aa3b, v28
	v_exp_f32_e32 v28, v28
	v_add_f32_e32 v21, v20, v33
	v_add_f32_e32 v21, v26, v21
	v_add_f32_e32 v21, v27, v21
	v_cvt_pk_bf16_f32 v20, v20, v26
	v_add_f32_e32 v29, v28, v21
	v_cvt_pk_bf16_f32 v21, v27, v28
	ds_write_b64 v65, v[20:21] offset:224
	v_sub_f32_e32 v20, v22, v18
	v_mul_f32_e32 v20, 0x3fb8aa3b, v20
	v_sub_f32_e32 v22, v23, v18
	v_exp_f32_e32 v20, v20
	v_mul_f32_e32 v22, 0x3fb8aa3b, v22
	v_sub_f32_e32 v23, v24, v18
	v_exp_f32_e32 v22, v22
	v_mul_f32_e32 v23, 0x3fb8aa3b, v23
	v_sub_f32_e32 v24, v25, v18
	v_exp_f32_e32 v23, v23
	v_mul_f32_e32 v24, 0x3fb8aa3b, v24
	v_exp_f32_e32 v24, v24
	v_add_f32_e32 v21, v20, v29
	v_add_f32_e32 v21, v22, v21
	v_add_f32_e32 v21, v23, v21
	v_cvt_pk_bf16_f32 v20, v20, v22
	v_add_f32_e32 v25, v24, v21
	v_cvt_pk_bf16_f32 v21, v23, v24
	ds_write_b64 v65, v[20:21] offset:256
	v_sub_f32_e32 v20, v83, v18
	v_mul_f32_e32 v20, 0x3fb8aa3b, v20
	v_sub_f32_e32 v19, v19, v18
	v_exp_f32_e32 v20, v20
	v_mul_f32_e32 v19, 0x3fb8aa3b, v19
	v_sub_f32_e32 v22, v82, v18
	v_exp_f32_e32 v19, v19
	v_mul_f32_e32 v22, 0x3fb8aa3b, v22
	v_sub_f32_e32 v23, v84, v18
	v_exp_f32_e32 v22, v22
	v_mul_f32_e32 v23, 0x3fb8aa3b, v23
	v_exp_f32_e32 v23, v23
	v_add_f32_e32 v21, v20, v25
	v_add_f32_e32 v21, v19, v21
	v_add_f32_e32 v21, v22, v21
	v_add_f32_e32 v24, v23, v21
	v_cvt_pk_bf16_f32 v20, v20, v19
	ds_bpermute_b32 v19, v74, v24
	v_cvt_pk_bf16_f32 v21, v22, v23
	ds_write_b64 v65, v[20:21] offset:288
	v_sub_f32_e32 v18, v81, v18
	v_mul_f32_e32 v18, 0x3fb8aa3b, v18
	s_waitcnt lgkmcnt(1)
; __device__ __forceinline__ unsigned cvt_pk_bf16(float lo, float hi) { unsigned r; asm volatile("v_cvt_pk_bf16_f32 %0, %1, %2" : "=v"(r) : "v"(lo), "v"(hi)); return r; }
; #define LAS __attribute__((address_space(3)))
; #define MFMA16(a, b, c) __builtin_amdgcn_mfma_f32_16x16x32_bf16((a), (b), (c), 0, 0, 0)
; #define LBAR() do { asm volatile("s_waitcnt lgkmcnt(0)" ::: "memory"); __builtin_amdgcn_s_barrier(); asm volatile("" ::: "memory"); } while (0)
; __device__ __forceinline__ void swa_compute(SwaRaw& R, int b, int kvh, int nb, const bf16_t* P, const float* __restrict__ qg, const float* __restrict__ kg, const float* __restrict__ sinks, bf16_t* OB, LAS unsigned char* lds, int tid) {
;     ...
;         sum += __shfl_xor(sum, 16); sum += __shfl_xor(sum, 32);
;         const float inv = 1.0f / (sum + __expf(sink - m));
;         asm volatile("s_waitcnt lgkmcnt(0)" ::: "memory"); __builtin_amdgcn_wave_barrier();
; #pragma unroll
;         for (int dt = 0; dt < 4; ++dt) { f32x4 acc = {0.f, 0.f, 0.f, 0.f};
; #pragma unroll
;             for (int ks = 0; ks < 5; ++ks) { const LAS bf16_t* vp = Vr + (kt0 * 16 + ks * 32 + 8 * fq + (fr >> 2)) * 72 + dt * 16 + 4 * (fr & 3);
;                 const v4i16_t lo = __builtin_amdgcn_ds_read_tr16_b64_v4i16((LAS v4i16_t*)vp), hi = __builtin_amdgcn_ds_read_tr16_b64_v4i16((LAS v4i16_t*)(vp + 4 * 72));
;                 const bf16x8 vf = {lo[0], lo[1], lo[2], lo[3], hi[0], hi[1], hi[2], hi[3]};
;                 acc = MFMA16(vf, ldfrag(Pw, 168, fr, ks * 32 + 8 * fq), acc); }
;             u32x2 w; w.x = cvt_pk_bf16(acc[0] * inv, acc[1] * inv); w.y = cvt_pk_bf16(acc[2] * inv, acc[3] * inv);
;             *(u32x2*)(OB + (rq0 + qi) * 1024 + hq * 64 + dt * 16 + 4 * fq) = w; }
;         LBAR();
;     }
	v_add_f32_e32 v19, v24, v19
	ds_bpermute_b32 v20, v75, v19
	v_exp_f32_e32 v18, v18
	v_add_u32_e32 v33, v165, v66
	v_add_u32_e32 v34, v65, v94
	s_waitcnt lgkmcnt(0)
	s_waitcnt lgkmcnt(0)
	v_add_f32_e32 v19, v19, v20
	v_add_f32_e32 v18, v18, v19
	v_div_scale_f32 v19, s[88:89], v18, v18, 1.0
	v_rcp_f32_e32 v20, v19
	s_nop 0
	v_fma_f32 v21, -v19, v20, 1.0
	v_fmac_f32_e32 v20, v21, v20
	v_div_scale_f32 v21, vcc, 1.0, v18, 1.0
	v_mul_f32_e32 v22, v21, v20
	v_fma_f32 v23, -v19, v22, v21
	v_fmac_f32_e32 v22, v23, v20
	v_fma_f32 v19, -v19, v22, v21
	v_div_fmas_f32 v19, v19, v20, v22
	ds_read_b64_tr_b16 v[20:21], v33 offset:55296
	ds_read_b64_tr_b16 v[22:23], v33 offset:55872
	ds_read_b128 v[24:27], v34
	s_waitcnt lgkmcnt(0)
	v_mfma_f32_16x16x32_bf16 v[20:23], v[20:23], v[24:27], 0
	ds_read_b64_tr_b16 v[24:25], v33 offset:59904
	ds_read_b64_tr_b16 v[26:27], v33 offset:60480
	ds_read_b128 v[28:31], v34 offset:64
	v_div_fixup_f32 v32, v19, v18, 1.0
	v_lshl_add_u64 v[18:19], v[60:61], 0, s[86:87]
	s_waitcnt lgkmcnt(0)
	v_mfma_f32_16x16x32_bf16 v[20:23], v[24:27], v[28:31], v[20:23]
	ds_read_b64_tr_b16 v[24:25], v33 offset:64512
	ds_read_b64_tr_b16 v[26:27], v33 offset:65088
	ds_read_b128 v[28:31], v34 offset:128
	s_add_u32 s86, s86, 0x80
	s_addc_u32 s87, s87, 0
	s_waitcnt lgkmcnt(0)
	v_mfma_f32_16x16x32_bf16 v[20:23], v[24:27], v[28:31], v[20:23]
	ds_read_b64_tr_b16 v[24:25], v79 offset:55296
	ds_read_b64_tr_b16 v[26:27], v79 offset:55872
	ds_read_b128 v[28:31], v34 offset:192
	s_add_u32 s2, s2, 4
	s_addc_u32 s3, s3, 0
	s_waitcnt lgkmcnt(0)
	v_mfma_f32_16x16x32_bf16 v[20:23], v[24:27], v[28:31], v[20:23]
	ds_read_b64_tr_b16 v[24:25], v80 offset:55296
	ds_read_b64_tr_b16 v[26:27], v80 offset:55872
	ds_read_b128 v[28:31], v34 offset:256
	s_cmpk_lg_i32 s86, 0x200
	s_waitcnt lgkmcnt(0)
	v_mfma_f32_16x16x32_bf16 v[20:23], v[24:27], v[28:31], v[20:23]
	s_nop 7
	v_mul_f32_e32 v20, v20, v32
	v_mul_f32_e32 v21, v21, v32
	v_cvt_pk_bf16_f32 v20, v20, v21
	v_mul_f32_e32 v21, v22, v32
	v_mul_f32_e32 v22, v23, v32
	v_cvt_pk_bf16_f32 v21, v21, v22
	global_store_dwordx2 v[18:19], v[20:21], off offset:-64
	ds_read_b64_tr_b16 v[20:21], v33 offset:55328
	ds_read_b64_tr_b16 v[22:23], v33 offset:55904
	ds_read_b128 v[24:27], v34
	s_waitcnt lgkmcnt(0)
	v_mfma_f32_16x16x32_bf16 v[20:23], v[20:23], v[24:27], 0
	ds_read_b64_tr_b16 v[24:25], v33 offset:59936
	ds_read_b64_tr_b16 v[26:27], v33 offset:60512
	ds_read_b128 v[28:31], v34 offset:64
	s_waitcnt lgkmcnt(0)
	v_mfma_f32_16x16x32_bf16 v[20:23], v[24:27], v[28:31], v[20:23]
	ds_read_b64_tr_b16 v[24:25], v33 offset:64544
	ds_read_b64_tr_b16 v[26:27], v33 offset:65120
	ds_read_b128 v[28:31], v34 offset:128
	s_waitcnt lgkmcnt(0)
	v_mfma_f32_16x16x32_bf16 v[20:23], v[24:27], v[28:31], v[20:23]
	ds_read_b64_tr_b16 v[24:25], v79 offset:55328
	ds_read_b64_tr_b16 v[26:27], v79 offset:55904
	ds_read_b128 v[28:31], v34 offset:192
	s_waitcnt lgkmcnt(0)
	v_mfma_f32_16x16x32_bf16 v[20:23], v[24:27], v[28:31], v[20:23]
	ds_read_b64_tr_b16 v[24:25], v80 offset:55328
	ds_read_b64_tr_b16 v[26:27], v80 offset:55904
	ds_read_b128 v[28:31], v34 offset:256
	s_waitcnt lgkmcnt(0)
	v_mfma_f32_16x16x32_bf16 v[20:23], v[24:27], v[28:31], v[20:23]
	s_nop 7
	v_mul_f32_e32 v20, v20, v32
	v_mul_f32_e32 v21, v21, v32
	v_cvt_pk_bf16_f32 v20, v20, v21
	v_mul_f32_e32 v21, v22, v32
	v_mul_f32_e32 v22, v23, v32
	v_cvt_pk_bf16_f32 v21, v21, v22
	global_store_dwordx2 v[18:19], v[20:21], off offset:-32
	ds_read_b64_tr_b16 v[20:21], v33 offset:55360
	ds_read_b64_tr_b16 v[22:23], v33 offset:55936
	ds_read_b128 v[24:27], v34
	s_waitcnt lgkmcnt(0)
	v_mfma_f32_16x16x32_bf16 v[20:23], v[20:23], v[24:27], 0
	ds_read_b64_tr_b16 v[24:25], v33 offset:59968
	ds_read_b64_tr_b16 v[26:27], v33 offset:60544
	ds_read_b128 v[28:31], v34 offset:64
	s_waitcnt lgkmcnt(0)
	v_mfma_f32_16x16x32_bf16 v[20:23], v[24:27], v[28:31], v[20:23]
	ds_read_b64_tr_b16 v[24:25], v33 offset:64576
	ds_read_b64_tr_b16 v[26:27], v33 offset:65152
	ds_read_b128 v[28:31], v34 offset:128
	s_waitcnt lgkmcnt(0)
	v_mfma_f32_16x16x32_bf16 v[20:23], v[24:27], v[28:31], v[20:23]
	ds_read_b64_tr_b16 v[24:25], v79 offset:55360
	ds_read_b64_tr_b16 v[26:27], v79 offset:55936
	ds_read_b128 v[28:31], v34 offset:192
	s_waitcnt lgkmcnt(0)
	v_mfma_f32_16x16x32_bf16 v[20:23], v[24:27], v[28:31], v[20:23]
	ds_read_b64_tr_b16 v[24:25], v80 offset:55360
	ds_read_b64_tr_b16 v[26:27], v80 offset:55936
	ds_read_b128 v[28:31], v34 offset:256
	s_waitcnt lgkmcnt(0)
	v_mfma_f32_16x16x32_bf16 v[20:23], v[24:27], v[28:31], v[20:23]
	s_nop 7
	v_mul_f32_e32 v20, v32, v20
	v_mul_f32_e32 v21, v32, v21
	v_cvt_pk_bf16_f32 v20, v20, v21
	v_mul_f32_e32 v21, v32, v22
	v_mul_f32_e32 v22, v32, v23
	v_cvt_pk_bf16_f32 v21, v21, v22
	global_store_dwordx2 v[18:19], v[20:21], off
	ds_read_b64_tr_b16 v[20:21], v33 offset:55392
	ds_read_b64_tr_b16 v[22:23], v33 offset:55968
	ds_read_b128 v[24:27], v34
	s_waitcnt lgkmcnt(0)
	v_mfma_f32_16x16x32_bf16 v[20:23], v[20:23], v[24:27], 0
	ds_read_b64_tr_b16 v[24:25], v33 offset:60000
	ds_read_b64_tr_b16 v[26:27], v33 offset:60576
	ds_read_b128 v[28:31], v34 offset:64
	s_waitcnt lgkmcnt(0)
	v_mfma_f32_16x16x32_bf16 v[20:23], v[24:27], v[28:31], v[20:23]
	ds_read_b64_tr_b16 v[24:25], v33 offset:64608
	ds_read_b64_tr_b16 v[26:27], v33 offset:65184
	ds_read_b128 v[28:31], v34 offset:128
	s_waitcnt lgkmcnt(0)
	v_mfma_f32_16x16x32_bf16 v[20:23], v[24:27], v[28:31], v[20:23]
	ds_read_b64_tr_b16 v[24:25], v79 offset:55392
	ds_read_b64_tr_b16 v[26:27], v79 offset:55968
	ds_read_b128 v[28:31], v34 offset:192
	s_waitcnt lgkmcnt(0)
	v_mfma_f32_16x16x32_bf16 v[20:23], v[24:27], v[28:31], v[20:23]
	ds_read_b64_tr_b16 v[24:25], v80 offset:55392
	ds_read_b64_tr_b16 v[26:27], v80 offset:55968
	ds_read_b128 v[28:31], v34 offset:256
	s_waitcnt lgkmcnt(0)
	v_mfma_f32_16x16x32_bf16 v[20:23], v[24:27], v[28:31], v[20:23]
	s_nop 7
	v_mul_f32_e32 v20, v32, v20
	v_mul_f32_e32 v21, v32, v21
	v_cvt_pk_bf16_f32 v20, v20, v21
	v_mul_f32_e32 v21, v32, v22
	v_mul_f32_e32 v22, v32, v23
	v_cvt_pk_bf16_f32 v21, v21, v22
	global_store_dwordx2 v[18:19], v[20:21], off offset:32
	s_waitcnt lgkmcnt(0)
	s_barrier
	s_cbranch_scc0 .LBB0_473
; __device__ __forceinline__ unsigned cvt_pk_bf16(float lo, float hi) { unsigned r; asm volatile("v_cvt_pk_bf16_f32 %0, %1, %2" : "=v"(r) : "v"(lo), "v"(hi)); return r; }
; __device__ __forceinline__ float bflo(unsigned w) { return __uint_as_float(w << 16); }
; __device__ __forceinline__ float bfhi(unsigned w) { return __uint_as_float(w & 0xffff0000u); }
; #define LAS __attribute__((address_space(3)))
; __device__ __forceinline__ void swa_compute(SwaRaw& R, int b, int kvh, int nb, const bf16_t* P, const float* __restrict__ qg, const float* __restrict__ kg, const float* __restrict__ sinks, bf16_t* OB, LAS unsigned char* lds, int tid) {
;     ...
;         for (int p = 0; p < 2; ++p) { const int row = (tid >> 3) + 64 * p; const u32x4 raw = R.q[p];
;             float x[8] = {bflo(raw.x), bfhi(raw.x), bflo(raw.y), bfhi(raw.y), bflo(raw.z), bfhi(raw.z), bflo(raw.w), bfhi(raw.w)};
;             float ss = 0.f;
; #pragma unroll
;             for (int e = 0; e < 8; ++e) ss += x[e] * x[e];
;             ss += __shfl_xor(ss, 1); ss += __shfl_xor(ss, 2); ss += __shfl_xor(ss, 4);
;             const float rs = 0.125f / sqrtf(ss * (1.0f / 64.0f) + EPS);
;             u32x4 w; w.x = cvt_pk_bf16(x[0] * rs * qg0.x, x[1] * rs * qg0.y); w.y = cvt_pk_bf16(x[2] * rs * qg0.z, x[3] * rs * qg0.w); w.z = cvt_pk_bf16(x[4] * rs * qg1.x, x[5] * rs * qg1.y); w.w = cvt_pk_bf16(x[6] * rs * qg1.z, x[7] * rs * qg1.w);
;             *(LAS u32x4*)(Qs + row * 72 + ch * 8) = w; }
;         if (g < 3) {
; #pragma unroll
;             for (int p = 0; p < 2; ++p) R.q[p] = *(const u32x4*)(P + (rq0 + (tid >> 3) + 64 * p) * PLD + 3072 + (hq + 1) * 64 + ch * 8);
.LBB0_499:
	s_waitcnt vmcnt(4)
	v_and_b32_e32 v21, 0xffff0000, v2
	v_lshlrev_b32_e32 v20, 16, v2
	v_mul_f32_e32 v28, v21, v21
	v_lshlrev_b32_e32 v24, 16, v3
	v_fmac_f32_e32 v28, v20, v20
	v_and_b32_e32 v25, 0xffff0000, v3
	v_fmac_f32_e32 v28, v24, v24
	v_lshlrev_b32_e32 v26, 16, v4
	v_fmac_f32_e32 v28, v25, v25
	v_and_b32_e32 v27, 0xffff0000, v4
	v_fmac_f32_e32 v28, v26, v26
	v_and_b32_e32 v22, 0xffff0000, v5
	v_lshlrev_b32_e32 v23, 16, v5
	v_fmac_f32_e32 v28, v27, v27
	v_pk_mul_f32 v[18:19], v[22:23], v[22:23]
	s_cmpk_eq_i32 s86, 0x180
	v_add_f32_e32 v19, v19, v28
	v_add_f32_e32 v18, v18, v19
	ds_bpermute_b32 v19, v62, v18
	s_waitcnt lgkmcnt(0)
	v_add_f32_e32 v18, v18, v19
	ds_bpermute_b32 v19, v63, v18
	s_waitcnt lgkmcnt(0)
	v_add_f32_e32 v18, v18, v19
	ds_bpermute_b32 v19, v64, v18
	s_waitcnt lgkmcnt(0)
	v_add_f32_e32 v18, v18, v19
	v_fmamk_f32 v18, v18, 0x3c800000, v95
	v_cmp_gt_f32_e32 vcc, s91, v18
	v_mul_f32_e32 v19, 0x4f800000, v18
	s_nop 0
	v_cndmask_b32_e32 v18, v18, v19, vcc
	v_sqrt_f32_e32 v19, v18
	s_nop 0
	v_add_u32_e32 v28, -1, v19
	v_fma_f32 v29, -v28, v19, v18
	v_cmp_ge_f32_e64 s[88:89], 0, v29
	v_add_u32_e32 v29, 1, v19
	s_nop 0
	v_cndmask_b32_e64 v28, v19, v28, s[88:89]
	v_fma_f32 v19, -v29, v19, v18
	v_cmp_lt_f32_e64 s[88:89], 0, v19
	s_nop 1
	v_cndmask_b32_e64 v19, v28, v29, s[88:89]
	v_mul_f32_e32 v28, 0x37800000, v19
	v_cndmask_b32_e32 v19, v19, v28, vcc
	v_cmp_class_f32_e32 vcc, v18, v172
	s_nop 1
	v_cndmask_b32_e32 v18, v19, v18, vcc
	v_div_scale_f32 v19, s[88:89], v18, v18, s93
	v_rcp_f32_e32 v28, v19
	s_nop 0
	v_fma_f32 v29, -v19, v28, 1.0
	v_fmac_f32_e32 v28, v29, v28
	v_div_scale_f32 v29, vcc, s93, v18, s93
	v_mul_f32_e32 v30, v29, v28
	v_fma_f32 v31, -v19, v30, v29
	v_fmac_f32_e32 v30, v31, v28
	v_fma_f32 v19, -v19, v30, v29
	v_div_fmas_f32 v19, v19, v28, v30
	v_div_fixup_f32 v28, v19, v18, s93
	v_mul_f32_e32 v18, v28, v20
	v_mul_f32_e32 v19, v28, v21
	v_mul_f32_e32 v18, v10, v18
	v_mul_f32_e32 v19, v11, v19
	v_cvt_pk_bf16_f32 v18, v18, v19
	v_mul_f32_e32 v19, v28, v24
	v_mul_f32_e32 v20, v28, v25
	v_mul_f32_e32 v19, v12, v19
	v_mul_f32_e32 v20, v13, v20
	v_cvt_pk_bf16_f32 v19, v19, v20
	v_mul_f32_e32 v20, v28, v26
	v_mul_f32_e32 v21, v28, v27
	v_mul_f32_e32 v20, v14, v20
	v_mul_f32_e32 v21, v15, v21
	v_cvt_pk_bf16_f32 v20, v20, v21
	v_mul_f32_e32 v21, v28, v23
	v_mul_f32_e32 v21, v16, v21
	v_mul_f32_e32 v22, v28, v22
	v_mul_f32_e32 v22, v17, v22
	v_cvt_pk_bf16_f32 v21, v21, v22
	ds_write_b128 v173, v[18:21]
	v_and_b32_e32 v21, 0xffff0000, v6
	v_lshlrev_b32_e32 v20, 16, v6
	v_mul_f32_e32 v28, v21, v21
	v_lshlrev_b32_e32 v24, 16, v7
	v_fmac_f32_e32 v28, v20, v20
	v_and_b32_e32 v25, 0xffff0000, v7
	v_fmac_f32_e32 v28, v24, v24
	v_lshlrev_b32_e32 v26, 16, v8
	v_fmac_f32_e32 v28, v25, v25
	v_and_b32_e32 v27, 0xffff0000, v8
	v_fmac_f32_e32 v28, v26, v26
	v_and_b32_e32 v22, 0xffff0000, v9
	v_lshlrev_b32_e32 v23, 16, v9
	v_fmac_f32_e32 v28, v27, v27
	v_pk_mul_f32 v[18:19], v[22:23], v[22:23]
	s_nop 0
	v_add_f32_e32 v19, v19, v28
	v_add_f32_e32 v18, v18, v19
	ds_bpermute_b32 v19, v62, v18
	s_waitcnt lgkmcnt(0)
	v_add_f32_e32 v18, v18, v19
	ds_bpermute_b32 v19, v63, v18
	s_waitcnt lgkmcnt(0)
	v_add_f32_e32 v18, v18, v19
	ds_bpermute_b32 v19, v64, v18
	s_waitcnt lgkmcnt(0)
	v_add_f32_e32 v18, v18, v19
	v_fmamk_f32 v18, v18, 0x3c800000, v95
	v_cmp_gt_f32_e32 vcc, s91, v18
	v_mul_f32_e32 v19, 0x4f800000, v18
	s_nop 0
	v_cndmask_b32_e32 v18, v18, v19, vcc
	v_sqrt_f32_e32 v19, v18
	s_nop 0
	v_add_u32_e32 v28, -1, v19
	v_fma_f32 v29, -v28, v19, v18
	v_cmp_ge_f32_e64 s[88:89], 0, v29
	v_add_u32_e32 v29, 1, v19
	s_nop 0
	v_cndmask_b32_e64 v28, v19, v28, s[88:89]
	v_fma_f32 v19, -v29, v19, v18
	v_cmp_lt_f32_e64 s[88:89], 0, v19
	s_nop 1
	v_cndmask_b32_e64 v19, v28, v29, s[88:89]
	v_mul_f32_e32 v28, 0x37800000, v19
	v_cndmask_b32_e32 v19, v19, v28, vcc
	v_cmp_class_f32_e32 vcc, v18, v172
	s_nop 1
	v_cndmask_b32_e32 v18, v19, v18, vcc
	v_div_scale_f32 v19, s[88:89], v18, v18, s93
	v_rcp_f32_e32 v28, v19
	s_nop 0
	v_fma_f32 v29, -v19, v28, 1.0
	v_fmac_f32_e32 v28, v29, v28
	v_div_scale_f32 v29, vcc, s93, v18, s93
	v_mul_f32_e32 v30, v29, v28
	v_fma_f32 v31, -v19, v30, v29
	v_fmac_f32_e32 v30, v31, v28
	v_fma_f32 v19, -v19, v30, v29
	v_div_fmas_f32 v19, v19, v28, v30
	v_div_fixup_f32 v28, v19, v18, s93
	v_mul_f32_e32 v18, v28, v20
	v_mul_f32_e32 v19, v28, v21
	v_mul_f32_e32 v18, v10, v18
	v_mul_f32_e32 v19, v11, v19
	v_cvt_pk_bf16_f32 v18, v18, v19
	v_mul_f32_e32 v19, v28, v24
	v_mul_f32_e32 v20, v28, v25
	v_mul_f32_e32 v19, v12, v19
	v_mul_f32_e32 v20, v13, v20
	v_cvt_pk_bf16_f32 v19, v19, v20
	v_mul_f32_e32 v20, v28, v26
	v_mul_f32_e32 v21, v28, v27
	v_mul_f32_e32 v20, v14, v20
	v_mul_f32_e32 v21, v15, v21
	v_cvt_pk_bf16_f32 v20, v20, v21
	v_mul_f32_e32 v21, v28, v23
	v_mul_f32_e32 v21, v16, v21
	v_mul_f32_e32 v22, v28, v22
	v_mul_f32_e32 v22, v17, v22
	v_cvt_pk_bf16_f32 v21, v21, v22
	ds_write_b128 v173, v[18:21] offset:9216
	s_cbranch_scc1 .LBB0_498
	v_lshl_add_u64 v[2:3], v[58:59], 0, s[86:87]
	v_add_co_u32_e32 v4, vcc, 0xb801000, v2
	s_nop 1
	v_addc_co_u32_e32 v5, vcc, 0, v3, vcc
	v_add_co_u32_e32 v6, vcc, 0xb911000, v2
	s_nop 1
	v_addc_co_u32_e32 v7, vcc, 0, v3, vcc
	global_load_dwordx4 v[2:5], v[4:5], off offset:2176
	s_nop 0
	global_load_dwordx4 v[6:9], v[6:7], off offset:2176
	s_branch .LBB0_498
